# units after the first skip the accumulator zeroing: first MFMA per accumulator in the peeled first K-iteration takes SrcC = 0
# speedup vs baseline: 1.0118x; 1.0118x over previous
.LBB0_258:
	s_ashr_i32 s93, s92, 31
	s_lshl_b64 s[22:23], s[92:93], 19
	s_add_u32 s22, s78, s22
	s_addc_u32 s23, s79, s23
	s_and_b64 s[52:53], s[6:7], exec
	s_cselect_b32 s60, s23, s99
	s_cselect_b32 s93, s22, s98
	s_ashr_i32 s47, s46, 31
	s_lshl_b64 s[52:53], s[46:47], 19
	s_add_u32 s94, s19, s52
	s_addc_u32 s95, s62, s53
	s_and_b64 s[52:53], s[6:7], exec
	s_cselect_b32 s47, s95, s51
	s_cselect_b32 vcc_lo, s94, s50
	s_add_u32 s98, s98, 0x40080
	s_addc_u32 s99, s99, 0
	s_add_u32 vcc_hi, s50, 0x100
	v_mov_b32_e32 v2, 0
	s_addc_u32 s70, s51, 0
	s_mov_b32 s71, -2
	v_readlane_b32 s50, v253, 0
	s_nop 1
	s_cmp_eq_u32 s50, 0
	s_cbranch_scc0 .Lpz_kvq
	v_mov_b32_e32 v3, v2
	v_mov_b32_e32 v4, v2
	v_mov_b32_e32 v5, v2
	v_mov_b32_e32 v6, v2
	v_mov_b32_e32 v7, v2
	v_mov_b32_e32 v8, v2
	v_mov_b32_e32 v9, v2
	v_mov_b32_e32 v14, v2
	v_mov_b32_e32 v15, v2
	v_mov_b32_e32 v16, v2
	v_mov_b32_e32 v17, v2
	v_mov_b32_e32 v22, v2
	v_mov_b32_e32 v23, v2
	v_mov_b32_e32 v24, v2
	v_mov_b32_e32 v25, v2
	v_mov_b32_e32 v30, v2
	v_mov_b32_e32 v31, v2
	v_mov_b32_e32 v32, v2
	v_mov_b32_e32 v33, v2
	v_mov_b32_e32 v38, v2
	v_mov_b32_e32 v39, v2
	v_mov_b32_e32 v40, v2
	v_mov_b32_e32 v41, v2
	v_mov_b32_e32 v46, v2
	v_mov_b32_e32 v47, v2
	v_mov_b32_e32 v48, v2
	v_mov_b32_e32 v49, v2
	v_mov_b32_e32 v54, v2
	v_mov_b32_e32 v55, v2
	v_mov_b32_e32 v56, v2
	v_mov_b32_e32 v57, v2
	v_mov_b32_e32 v10, v2
	v_mov_b32_e32 v11, v2
	v_mov_b32_e32 v12, v2
	v_mov_b32_e32 v13, v2
	v_mov_b32_e32 v18, v2
	v_mov_b32_e32 v19, v2
	v_mov_b32_e32 v20, v2
	v_mov_b32_e32 v21, v2
	v_mov_b32_e32 v26, v2
	v_mov_b32_e32 v27, v2
	v_mov_b32_e32 v28, v2
	v_mov_b32_e32 v29, v2
	v_mov_b32_e32 v34, v2
	v_mov_b32_e32 v35, v2
	v_mov_b32_e32 v36, v2
	v_mov_b32_e32 v37, v2
	v_mov_b32_e32 v42, v2
	v_mov_b32_e32 v43, v2
	v_mov_b32_e32 v44, v2
	v_mov_b32_e32 v45, v2
	v_mov_b32_e32 v50, v2
	v_mov_b32_e32 v51, v2
	v_mov_b32_e32 v52, v2
	v_mov_b32_e32 v53, v2
	v_mov_b32_e32 v58, v2
	v_mov_b32_e32 v59, v2
	v_mov_b32_e32 v60, v2
	v_mov_b32_e32 v61, v2
	v_mov_b32_e32 v62, v2
	v_mov_b32_e32 v63, v2
	v_mov_b32_e32 v64, v2
	v_mov_b32_e32 v65, v2
	v_mov_b32_e32 v66, v2
	v_mov_b32_e32 v67, v2
	v_mov_b32_e32 v68, v2
	v_mov_b32_e32 v69, v2
	v_mov_b32_e32 v70, v2
	v_mov_b32_e32 v71, v2
	v_mov_b32_e32 v72, v2
	v_mov_b32_e32 v73, v2
	v_mov_b32_e32 v78, v2
	v_mov_b32_e32 v79, v2
	v_mov_b32_e32 v80, v2
	v_mov_b32_e32 v81, v2
	v_mov_b32_e32 v86, v2
	v_mov_b32_e32 v87, v2
	v_mov_b32_e32 v88, v2
	v_mov_b32_e32 v89, v2
	v_mov_b32_e32 v94, v2
	v_mov_b32_e32 v95, v2
	v_mov_b32_e32 v96, v2
	v_mov_b32_e32 v97, v2
	v_mov_b32_e32 v102, v2
	v_mov_b32_e32 v103, v2
	v_mov_b32_e32 v104, v2
	v_mov_b32_e32 v105, v2
	v_mov_b32_e32 v110, v2
	v_mov_b32_e32 v111, v2
	v_mov_b32_e32 v112, v2
	v_mov_b32_e32 v113, v2
	v_mov_b32_e32 v118, v2
	v_mov_b32_e32 v119, v2
	v_mov_b32_e32 v120, v2
	v_mov_b32_e32 v121, v2
	v_mov_b32_e32 v74, v2
	v_mov_b32_e32 v75, v2
	v_mov_b32_e32 v76, v2
	v_mov_b32_e32 v77, v2
	v_mov_b32_e32 v82, v2
	v_mov_b32_e32 v83, v2
	v_mov_b32_e32 v84, v2
	v_mov_b32_e32 v85, v2
	v_mov_b32_e32 v90, v2
	v_mov_b32_e32 v91, v2
	v_mov_b32_e32 v92, v2
	v_mov_b32_e32 v93, v2
	v_mov_b32_e32 v98, v2
	v_mov_b32_e32 v99, v2
	v_mov_b32_e32 v100, v2
	v_mov_b32_e32 v101, v2
	v_mov_b32_e32 v106, v2
	v_mov_b32_e32 v107, v2
	v_mov_b32_e32 v108, v2
	v_mov_b32_e32 v109, v2
	v_mov_b32_e32 v114, v2
	v_mov_b32_e32 v115, v2
	v_mov_b32_e32 v116, v2
	v_mov_b32_e32 v117, v2
	v_mov_b32_e32 v122, v2
	v_mov_b32_e32 v123, v2
	v_mov_b32_e32 v124, v2
	v_mov_b32_e32 v125, v2
	v_mov_b32_e32 v126, v2
	v_mov_b32_e32 v127, v2
	v_mov_b32_e32 v128, v2
	v_mov_b32_e32 v129, v2
	s_branch .LBB0_259
.Lpz_kvq:
	s_add_u32 s50, s98, 0xfffc0080
	s_addc_u32 s51, s99, -1
	s_add_i32 s72, 0, 0x10000
	s_cmp_eq_u32 s71, 12
	s_cselect_b32 s53, s60, s51
	s_cselect_b32 s52, s93, s50
	v_add_u32_e32 v162, s72, v159
	s_cselect_b32 s51, s47, s70
	s_cselect_b32 s50, vcc_lo, vcc_hi
	s_add_i32 s41, 0, 0x14000
	ds_read_b128 v[154:157], v162
	ds_read_b128 v[178:181], v162 offset:1024
	ds_read_b128 v[182:185], v162 offset:2048
	ds_read_b128 v[186:189], v162 offset:3072
	v_add_u32_e32 v162, s41, v159
	ds_read_b128 v[190:193], v162
	ds_read_b128 v[194:197], v162 offset:1024
	ds_read_b128 v[198:201], v162 offset:2048
	ds_read_b128 v[202:205], v162 offset:3072
	v_lshl_add_u64 v[164:165], s[98:99], 0, v[150:151]
	s_add_i32 m0, s27, 0xc000
	ds_read_b128 v[206:209], v161
	ds_read_b128 v[210:213], v161 offset:1024
	ds_read_b128 v[214:217], v161 offset:2048
	ds_read_b128 v[218:221], v161 offset:3072
	ds_read_b128 v[222:225], v161 offset:4096
	ds_read_b128 v[226:229], v161 offset:5120
	ds_read_b128 v[230:233], v161 offset:6144
	ds_read_b128 v[234:237], v161 offset:7168
	global_load_lds_dwordx4 v[164:165], off
	v_lshl_add_u64 v[164:165], s[98:99], 0, v[152:153]
	s_add_i32 m0, s27, 0xe000
	s_nop 0
	global_load_lds_dwordx4 v[164:165], off
	s_waitcnt vmcnt(24)
	s_waitcnt lgkmcnt(0)
	s_barrier
	s_setprio 1
	s_waitcnt lgkmcnt(0)
	v_mfma_f32_16x16x32_bf16 v[126:129], v[154:157], v[206:209], 0
	v_mfma_f32_16x16x32_bf16 v[122:125], v[182:185], v[206:209], 0
	v_mfma_f32_16x16x32_bf16 v[114:117], v[154:157], v[214:217], 0
	v_mfma_f32_16x16x32_bf16 v[106:109], v[182:185], v[214:217], 0
	v_mfma_f32_16x16x32_bf16 v[98:101], v[154:157], v[222:225], 0
	v_mfma_f32_16x16x32_bf16 v[90:93], v[182:185], v[222:225], 0
	v_mfma_f32_16x16x32_bf16 v[82:85], v[154:157], v[230:233], 0
	v_mfma_f32_16x16x32_bf16 v[74:77], v[182:185], v[230:233], 0
	v_mfma_f32_16x16x32_bf16 v[126:129], v[178:181], v[210:213], v[126:129]
	v_mfma_f32_16x16x32_bf16 v[122:125], v[186:189], v[210:213], v[122:125]
	v_mfma_f32_16x16x32_bf16 v[114:117], v[178:181], v[218:221], v[114:117]
	v_mfma_f32_16x16x32_bf16 v[106:109], v[186:189], v[218:221], v[106:109]
	v_mfma_f32_16x16x32_bf16 v[98:101], v[178:181], v[226:229], v[98:101]
	v_mfma_f32_16x16x32_bf16 v[90:93], v[186:189], v[226:229], v[90:93]
	v_mfma_f32_16x16x32_bf16 v[82:85], v[178:181], v[234:237], v[82:85]
	v_mfma_f32_16x16x32_bf16 v[74:77], v[186:189], v[234:237], v[74:77]
	s_setprio 0
	s_setprio 1
	v_mfma_f32_16x16x32_bf16 v[118:121], v[190:193], v[206:209], 0
	v_mfma_f32_16x16x32_bf16 v[110:113], v[198:201], v[206:209], 0
	v_mfma_f32_16x16x32_bf16 v[102:105], v[190:193], v[214:217], 0
	v_mfma_f32_16x16x32_bf16 v[94:97], v[198:201], v[214:217], 0
	v_mfma_f32_16x16x32_bf16 v[86:89], v[190:193], v[222:225], 0
	v_mfma_f32_16x16x32_bf16 v[78:81], v[198:201], v[222:225], 0
	v_mfma_f32_16x16x32_bf16 v[70:73], v[190:193], v[230:233], 0
	v_mfma_f32_16x16x32_bf16 v[66:69], v[198:201], v[230:233], 0
	v_mfma_f32_16x16x32_bf16 v[118:121], v[194:197], v[210:213], v[118:121]
	v_mfma_f32_16x16x32_bf16 v[110:113], v[202:205], v[210:213], v[110:113]
	v_mfma_f32_16x16x32_bf16 v[102:105], v[194:197], v[218:221], v[102:105]
	v_mfma_f32_16x16x32_bf16 v[94:97], v[202:205], v[218:221], v[94:97]
	s_setprio 2
	s_barrier
	v_mfma_f32_16x16x32_bf16 v[86:89], v[194:197], v[226:229], v[86:89]
	v_mfma_f32_16x16x32_bf16 v[78:81], v[202:205], v[226:229], v[78:81]
	v_mfma_f32_16x16x32_bf16 v[70:73], v[194:197], v[234:237], v[70:73]
	v_mfma_f32_16x16x32_bf16 v[66:69], v[202:205], v[234:237], v[66:69]
	s_setprio 0
	s_add_i32 s72, s72, s65
	v_lshl_add_u64 v[164:165], s[50:51], 0, v[146:147]
	s_mov_b32 m0, s72
	ds_read_b128 v[206:209], v161 offset:16384
	ds_read_b128 v[210:213], v161 offset:17408
	ds_read_b128 v[214:217], v161 offset:18432
	ds_read_b128 v[218:221], v161 offset:19456
	ds_read_b128 v[222:225], v161 offset:20480
	ds_read_b128 v[226:229], v161 offset:21504
	ds_read_b128 v[230:233], v161 offset:22528
	ds_read_b128 v[234:237], v161 offset:23552
	global_load_lds_dwordx4 v[164:165], off
	s_add_i32 m0, s72, 0x2000
	s_add_u32 s72, s50, 0x40000
	v_lshl_add_u64 v[238:239], s[50:51], 0, v[132:133]
	s_addc_u32 s73, s51, 0
	s_add_i32 s41, s41, s65
	global_load_lds_dwordx4 v[238:239], off
	v_lshl_add_u64 v[240:241], s[72:73], 0, v[146:147]
	s_mov_b32 m0, s41
	v_lshl_add_u64 v[242:243], s[52:53], 0, v[144:145]
	global_load_lds_dwordx4 v[240:241], off
	v_lshl_add_u64 v[240:241], s[72:73], 0, v[132:133]
	s_add_i32 m0, s41, 0x2000
	s_nop 0
	global_load_lds_dwordx4 v[240:241], off
	v_lshl_add_u64 v[240:241], s[52:53], 0, v[148:149]
	s_mov_b32 m0, s27
	s_nop 0
	global_load_lds_dwordx4 v[240:241], off
	s_mov_b32 m0, s74
	s_nop 0
	global_load_lds_dwordx4 v[242:243], off
	s_waitcnt vmcnt(24)
	s_waitcnt lgkmcnt(0)
	s_barrier
	s_setprio 1
	s_waitcnt lgkmcnt(0)
	v_mfma_f32_16x16x32_bf16 v[62:65], v[154:157], v[206:209], 0
	v_mfma_f32_16x16x32_bf16 v[58:61], v[182:185], v[206:209], 0
	v_mfma_f32_16x16x32_bf16 v[50:53], v[154:157], v[214:217], 0
	v_mfma_f32_16x16x32_bf16 v[42:45], v[182:185], v[214:217], 0
	v_mfma_f32_16x16x32_bf16 v[34:37], v[154:157], v[222:225], 0
	v_mfma_f32_16x16x32_bf16 v[26:29], v[182:185], v[222:225], 0
	v_mfma_f32_16x16x32_bf16 v[18:21], v[154:157], v[230:233], 0
	v_mfma_f32_16x16x32_bf16 v[10:13], v[182:185], v[230:233], 0
	v_mfma_f32_16x16x32_bf16 v[62:65], v[178:181], v[210:213], v[62:65]
	v_mfma_f32_16x16x32_bf16 v[58:61], v[186:189], v[210:213], v[58:61]
	v_mfma_f32_16x16x32_bf16 v[50:53], v[178:181], v[218:221], v[50:53]
	v_mfma_f32_16x16x32_bf16 v[42:45], v[186:189], v[218:221], v[42:45]
	v_mfma_f32_16x16x32_bf16 v[34:37], v[178:181], v[226:229], v[34:37]
	v_mfma_f32_16x16x32_bf16 v[26:29], v[186:189], v[226:229], v[26:29]
	v_mfma_f32_16x16x32_bf16 v[18:21], v[178:181], v[234:237], v[18:21]
	v_mfma_f32_16x16x32_bf16 v[10:13], v[186:189], v[234:237], v[10:13]
	s_setprio 0
	s_setprio 1
	v_mfma_f32_16x16x32_bf16 v[54:57], v[190:193], v[206:209], 0
	v_mfma_f32_16x16x32_bf16 v[46:49], v[198:201], v[206:209], 0
	v_mfma_f32_16x16x32_bf16 v[38:41], v[190:193], v[214:217], 0
	v_mfma_f32_16x16x32_bf16 v[30:33], v[198:201], v[214:217], 0
	v_mfma_f32_16x16x32_bf16 v[22:25], v[190:193], v[222:225], 0
	v_mfma_f32_16x16x32_bf16 v[14:17], v[198:201], v[222:225], 0
	v_mfma_f32_16x16x32_bf16 v[6:9], v[190:193], v[230:233], 0
	v_mfma_f32_16x16x32_bf16 v[2:5], v[198:201], v[230:233], 0
	v_mfma_f32_16x16x32_bf16 v[54:57], v[194:197], v[210:213], v[54:57]
	v_mfma_f32_16x16x32_bf16 v[46:49], v[202:205], v[210:213], v[46:49]
	v_mfma_f32_16x16x32_bf16 v[38:41], v[194:197], v[218:221], v[38:41]
	v_mfma_f32_16x16x32_bf16 v[30:33], v[202:205], v[218:221], v[30:33]
	s_setprio 2
	s_barrier
	v_mfma_f32_16x16x32_bf16 v[22:25], v[194:197], v[226:229], v[22:25]
	v_mfma_f32_16x16x32_bf16 v[14:17], v[202:205], v[226:229], v[14:17]
	v_mfma_f32_16x16x32_bf16 v[6:9], v[194:197], v[234:237], v[6:9]
	v_mfma_f32_16x16x32_bf16 v[2:5], v[202:205], v[234:237], v[2:5]
	s_setprio 0
	s_add_i32 s41, 0, 0x18000
	v_add_u32_e32 v162, s41, v159
	s_add_i32 s72, 0, 0x1c000
	ds_read_b128 v[154:157], v162
	ds_read_b128 v[178:181], v162 offset:1024
	ds_read_b128 v[182:185], v162 offset:2048
	ds_read_b128 v[186:189], v162 offset:3072
	v_add_u32_e32 v162, s72, v159
	ds_read_b128 v[190:193], v162
	ds_read_b128 v[194:197], v162 offset:1024
	ds_read_b128 v[198:201], v162 offset:2048
	ds_read_b128 v[202:205], v162 offset:3072
	s_add_u32 s52, s52, 0x40000
	s_addc_u32 s53, s53, 0
	s_mov_b32 m0, s75
	v_lshl_add_u64 v[244:245], s[52:53], 0, v[148:149]
	ds_read_b128 v[206:209], v161 offset:32768
	ds_read_b128 v[210:213], v161 offset:33792
	ds_read_b128 v[214:217], v161 offset:34816
	ds_read_b128 v[218:221], v161 offset:35840
	ds_read_b128 v[222:225], v161 offset:36864
	ds_read_b128 v[226:229], v161 offset:37888
	ds_read_b128 v[230:233], v161 offset:38912
	ds_read_b128 v[234:237], v161 offset:39936
	global_load_lds_dwordx4 v[244:245], off
	v_lshl_add_u64 v[244:245], s[52:53], 0, v[144:145]
	s_mov_b32 m0, s97
	s_nop 0
	global_load_lds_dwordx4 v[244:245], off
	s_waitcnt vmcnt(8)
	s_waitcnt lgkmcnt(0)
	s_barrier
	s_setprio 1
	s_waitcnt lgkmcnt(0)
	v_mfma_f32_16x16x32_bf16 v[126:129], v[154:157], v[206:209], v[126:129]
	v_mfma_f32_16x16x32_bf16 v[122:125], v[182:185], v[206:209], v[122:125]
	v_mfma_f32_16x16x32_bf16 v[114:117], v[154:157], v[214:217], v[114:117]
	v_mfma_f32_16x16x32_bf16 v[106:109], v[182:185], v[214:217], v[106:109]
	v_mfma_f32_16x16x32_bf16 v[98:101], v[154:157], v[222:225], v[98:101]
	v_mfma_f32_16x16x32_bf16 v[90:93], v[182:185], v[222:225], v[90:93]
	v_mfma_f32_16x16x32_bf16 v[82:85], v[154:157], v[230:233], v[82:85]
	v_mfma_f32_16x16x32_bf16 v[74:77], v[182:185], v[230:233], v[74:77]
	v_mfma_f32_16x16x32_bf16 v[126:129], v[178:181], v[210:213], v[126:129]
	v_mfma_f32_16x16x32_bf16 v[122:125], v[186:189], v[210:213], v[122:125]
	v_mfma_f32_16x16x32_bf16 v[114:117], v[178:181], v[218:221], v[114:117]
	v_mfma_f32_16x16x32_bf16 v[106:109], v[186:189], v[218:221], v[106:109]
	v_mfma_f32_16x16x32_bf16 v[98:101], v[178:181], v[226:229], v[98:101]
	v_mfma_f32_16x16x32_bf16 v[90:93], v[186:189], v[226:229], v[90:93]
	v_mfma_f32_16x16x32_bf16 v[82:85], v[178:181], v[234:237], v[82:85]
	v_mfma_f32_16x16x32_bf16 v[74:77], v[186:189], v[234:237], v[74:77]
	s_setprio 0
	s_setprio 1
	v_mfma_f32_16x16x32_bf16 v[118:121], v[190:193], v[206:209], v[118:121]
	v_mfma_f32_16x16x32_bf16 v[110:113], v[198:201], v[206:209], v[110:113]
	v_mfma_f32_16x16x32_bf16 v[102:105], v[190:193], v[214:217], v[102:105]
	v_mfma_f32_16x16x32_bf16 v[94:97], v[198:201], v[214:217], v[94:97]
	v_mfma_f32_16x16x32_bf16 v[86:89], v[190:193], v[222:225], v[86:89]
	v_mfma_f32_16x16x32_bf16 v[78:81], v[198:201], v[222:225], v[78:81]
	v_mfma_f32_16x16x32_bf16 v[70:73], v[190:193], v[230:233], v[70:73]
	v_mfma_f32_16x16x32_bf16 v[66:69], v[198:201], v[230:233], v[66:69]
	v_mfma_f32_16x16x32_bf16 v[118:121], v[194:197], v[210:213], v[118:121]
	v_mfma_f32_16x16x32_bf16 v[110:113], v[202:205], v[210:213], v[110:113]
	v_mfma_f32_16x16x32_bf16 v[102:105], v[194:197], v[218:221], v[102:105]
	v_mfma_f32_16x16x32_bf16 v[94:97], v[202:205], v[218:221], v[94:97]
	s_setprio 2
	s_barrier
	v_mfma_f32_16x16x32_bf16 v[86:89], v[194:197], v[226:229], v[86:89]
	v_mfma_f32_16x16x32_bf16 v[78:81], v[202:205], v[226:229], v[78:81]
	v_mfma_f32_16x16x32_bf16 v[70:73], v[194:197], v[234:237], v[70:73]
	v_mfma_f32_16x16x32_bf16 v[66:69], v[202:205], v[234:237], v[66:69]
	s_setprio 0
	s_add_i32 s41, s41, s65
	v_lshl_add_u64 v[164:165], v[164:165], 0, s[66:67]
	s_mov_b32 m0, s41
	ds_read_b128 v[206:209], v161 offset:49152
	ds_read_b128 v[210:213], v161 offset:50176
	ds_read_b128 v[214:217], v161 offset:51200
	ds_read_b128 v[218:221], v161 offset:52224
	ds_read_b128 v[222:225], v161 offset:53248
	ds_read_b128 v[226:229], v161 offset:54272
	ds_read_b128 v[230:233], v161 offset:55296
	ds_read_b128 v[234:237], v161 offset:56320
	global_load_lds_dwordx4 v[164:165], off
	s_add_i32 m0, s41, 0x2000
	s_add_u32 s50, s50, 0x40080
	v_lshl_add_u64 v[164:165], v[238:239], 0, s[66:67]
	s_addc_u32 s51, s51, 0
	s_add_i32 s41, s72, s65
	global_load_lds_dwordx4 v[164:165], off
	v_lshl_add_u64 v[164:165], s[50:51], 0, v[146:147]
	s_mov_b32 m0, s41
	s_nop 0
	global_load_lds_dwordx4 v[164:165], off
	v_lshl_add_u64 v[164:165], s[50:51], 0, v[132:133]
	s_add_i32 m0, s41, 0x2000
	s_nop 0
	global_load_lds_dwordx4 v[164:165], off
	v_lshl_add_u64 v[164:165], v[240:241], 0, s[66:67]
	s_mov_b32 m0, s24
	s_nop 0
	global_load_lds_dwordx4 v[164:165], off
	v_lshl_add_u64 v[164:165], v[242:243], 0, s[66:67]
	s_mov_b32 m0, s25
	s_nop 0
	global_load_lds_dwordx4 v[164:165], off
	s_waitcnt vmcnt(8)
	s_waitcnt lgkmcnt(0)
	s_barrier
	s_setprio 1
	s_waitcnt lgkmcnt(0)
	v_mfma_f32_16x16x32_bf16 v[62:65], v[154:157], v[206:209], v[62:65]
	v_mfma_f32_16x16x32_bf16 v[58:61], v[182:185], v[206:209], v[58:61]
	v_mfma_f32_16x16x32_bf16 v[50:53], v[154:157], v[214:217], v[50:53]
	v_mfma_f32_16x16x32_bf16 v[42:45], v[182:185], v[214:217], v[42:45]
	v_mfma_f32_16x16x32_bf16 v[34:37], v[154:157], v[222:225], v[34:37]
	v_mfma_f32_16x16x32_bf16 v[26:29], v[182:185], v[222:225], v[26:29]
	v_mfma_f32_16x16x32_bf16 v[18:21], v[154:157], v[230:233], v[18:21]
	v_mfma_f32_16x16x32_bf16 v[10:13], v[182:185], v[230:233], v[10:13]
	v_mfma_f32_16x16x32_bf16 v[62:65], v[178:181], v[210:213], v[62:65]
	v_mfma_f32_16x16x32_bf16 v[58:61], v[186:189], v[210:213], v[58:61]
	v_mfma_f32_16x16x32_bf16 v[50:53], v[178:181], v[218:221], v[50:53]
	v_mfma_f32_16x16x32_bf16 v[42:45], v[186:189], v[218:221], v[42:45]
	v_mfma_f32_16x16x32_bf16 v[34:37], v[178:181], v[226:229], v[34:37]
	v_mfma_f32_16x16x32_bf16 v[26:29], v[186:189], v[226:229], v[26:29]
	v_mfma_f32_16x16x32_bf16 v[18:21], v[178:181], v[234:237], v[18:21]
	v_mfma_f32_16x16x32_bf16 v[10:13], v[186:189], v[234:237], v[10:13]
	s_setprio 0
	s_setprio 1
	v_mfma_f32_16x16x32_bf16 v[54:57], v[190:193], v[206:209], v[54:57]
	v_mfma_f32_16x16x32_bf16 v[46:49], v[198:201], v[206:209], v[46:49]
	v_mfma_f32_16x16x32_bf16 v[38:41], v[190:193], v[214:217], v[38:41]
	v_mfma_f32_16x16x32_bf16 v[30:33], v[198:201], v[214:217], v[30:33]
	v_mfma_f32_16x16x32_bf16 v[22:25], v[190:193], v[222:225], v[22:25]
	v_mfma_f32_16x16x32_bf16 v[14:17], v[198:201], v[222:225], v[14:17]
	v_mfma_f32_16x16x32_bf16 v[6:9], v[190:193], v[230:233], v[6:9]
	v_mfma_f32_16x16x32_bf16 v[2:5], v[198:201], v[230:233], v[2:5]
	v_mfma_f32_16x16x32_bf16 v[54:57], v[194:197], v[210:213], v[54:57]
	v_mfma_f32_16x16x32_bf16 v[46:49], v[202:205], v[210:213], v[46:49]
	v_mfma_f32_16x16x32_bf16 v[38:41], v[194:197], v[218:221], v[38:41]
	v_mfma_f32_16x16x32_bf16 v[30:33], v[202:205], v[218:221], v[30:33]
	s_setprio 2
	s_barrier
	v_mfma_f32_16x16x32_bf16 v[22:25], v[194:197], v[226:229], v[22:25]
	v_mfma_f32_16x16x32_bf16 v[14:17], v[202:205], v[226:229], v[14:17]
	v_mfma_f32_16x16x32_bf16 v[6:9], v[194:197], v[234:237], v[6:9]
	v_mfma_f32_16x16x32_bf16 v[2:5], v[202:205], v[234:237], v[2:5]
	s_setprio 0
	s_add_i32 s71, s71, 2
	s_add_u32 s98, s98, 0x100
	s_addc_u32 s99, s99, 0
	s_add_u32 vcc_hi, vcc_hi, 0x100
	s_addc_u32 s70, s70, 0
	s_cmp_gt_u32 s71, 13

.LBB0_282:
	s_ashr_i32 s47, s46, 31
	s_lshl_b64 s[44:45], s[46:47], 19
	s_add_u32 s94, s78, s44
	s_addc_u32 s95, s79, s45
	s_and_b64 s[44:45], s[6:7], exec
	s_cselect_b32 s30, s95, s23
	s_cselect_b32 s37, s94, s22
	s_ashr_i32 s13, s12, 31
	s_lshl_b64 s[44:45], s[12:13], 19
	s_add_u32 s96, s4, s44
	s_addc_u32 s97, s5, s45
	s_and_b64 s[44:45], s[6:7], exec
	s_cselect_b32 s13, s97, s27
	s_cselect_b32 s47, s96, s26
	s_add_u32 s22, s22, 0x40080
	s_addc_u32 s23, s23, 0
	s_add_u32 s56, s26, 0x100
	v_mov_b32_e32 v2, 0
	s_addc_u32 s65, s27, 0
	s_mov_b32 s68, -2
	v_readlane_b32 s26, v253, 0
	s_nop 1
	s_cmp_eq_u32 s26, 0
	s_cbranch_scc0 .Lpz_up
	v_mov_b32_e32 v3, v2
	v_mov_b32_e32 v4, v2
	v_mov_b32_e32 v5, v2
	v_mov_b32_e32 v10, v2
	v_mov_b32_e32 v11, v2
	v_mov_b32_e32 v12, v2
	v_mov_b32_e32 v13, v2
	v_mov_b32_e32 v18, v2
	v_mov_b32_e32 v19, v2
	v_mov_b32_e32 v20, v2
	v_mov_b32_e32 v21, v2
	v_mov_b32_e32 v26, v2
	v_mov_b32_e32 v27, v2
	v_mov_b32_e32 v28, v2
	v_mov_b32_e32 v29, v2
	v_mov_b32_e32 v34, v2
	v_mov_b32_e32 v35, v2
	v_mov_b32_e32 v36, v2
	v_mov_b32_e32 v37, v2
	v_mov_b32_e32 v42, v2
	v_mov_b32_e32 v43, v2
	v_mov_b32_e32 v44, v2
	v_mov_b32_e32 v45, v2
	v_mov_b32_e32 v50, v2
	v_mov_b32_e32 v51, v2
	v_mov_b32_e32 v52, v2
	v_mov_b32_e32 v53, v2
	v_mov_b32_e32 v58, v2
	v_mov_b32_e32 v59, v2
	v_mov_b32_e32 v60, v2
	v_mov_b32_e32 v61, v2
	v_mov_b32_e32 v6, v2
	v_mov_b32_e32 v7, v2
	v_mov_b32_e32 v8, v2
	v_mov_b32_e32 v9, v2
	v_mov_b32_e32 v14, v2
	v_mov_b32_e32 v15, v2
	v_mov_b32_e32 v16, v2
	v_mov_b32_e32 v17, v2
	v_mov_b32_e32 v22, v2
	v_mov_b32_e32 v23, v2
	v_mov_b32_e32 v24, v2
	v_mov_b32_e32 v25, v2
	v_mov_b32_e32 v30, v2
	v_mov_b32_e32 v31, v2
	v_mov_b32_e32 v32, v2
	v_mov_b32_e32 v33, v2
	v_mov_b32_e32 v38, v2
	v_mov_b32_e32 v39, v2
	v_mov_b32_e32 v40, v2
	v_mov_b32_e32 v41, v2
	v_mov_b32_e32 v46, v2
	v_mov_b32_e32 v47, v2
	v_mov_b32_e32 v48, v2
	v_mov_b32_e32 v49, v2
	v_mov_b32_e32 v54, v2
	v_mov_b32_e32 v55, v2
	v_mov_b32_e32 v56, v2
	v_mov_b32_e32 v57, v2
	v_mov_b32_e32 v62, v2
	v_mov_b32_e32 v63, v2
	v_mov_b32_e32 v64, v2
	v_mov_b32_e32 v65, v2
	v_mov_b32_e32 v66, v2
	v_mov_b32_e32 v67, v2
	v_mov_b32_e32 v68, v2
	v_mov_b32_e32 v69, v2
	v_mov_b32_e32 v74, v2
	v_mov_b32_e32 v75, v2
	v_mov_b32_e32 v76, v2
	v_mov_b32_e32 v77, v2
	v_mov_b32_e32 v82, v2
	v_mov_b32_e32 v83, v2
	v_mov_b32_e32 v84, v2
	v_mov_b32_e32 v85, v2
	v_mov_b32_e32 v90, v2
	v_mov_b32_e32 v91, v2
	v_mov_b32_e32 v92, v2
	v_mov_b32_e32 v93, v2
	v_mov_b32_e32 v98, v2
	v_mov_b32_e32 v99, v2
	v_mov_b32_e32 v100, v2
	v_mov_b32_e32 v101, v2
	v_mov_b32_e32 v106, v2
	v_mov_b32_e32 v107, v2
	v_mov_b32_e32 v108, v2
	v_mov_b32_e32 v109, v2
	v_mov_b32_e32 v114, v2
	v_mov_b32_e32 v115, v2
	v_mov_b32_e32 v116, v2
	v_mov_b32_e32 v117, v2
	v_mov_b32_e32 v122, v2
	v_mov_b32_e32 v123, v2
	v_mov_b32_e32 v124, v2
	v_mov_b32_e32 v125, v2
	v_mov_b32_e32 v70, v2
	v_mov_b32_e32 v71, v2
	v_mov_b32_e32 v72, v2
	v_mov_b32_e32 v73, v2
	v_mov_b32_e32 v78, v2
	v_mov_b32_e32 v79, v2
	v_mov_b32_e32 v80, v2
	v_mov_b32_e32 v81, v2
	v_mov_b32_e32 v86, v2
	v_mov_b32_e32 v87, v2
	v_mov_b32_e32 v88, v2
	v_mov_b32_e32 v89, v2
	v_mov_b32_e32 v94, v2
	v_mov_b32_e32 v95, v2
	v_mov_b32_e32 v96, v2
	v_mov_b32_e32 v97, v2
	v_mov_b32_e32 v102, v2
	v_mov_b32_e32 v103, v2
	v_mov_b32_e32 v104, v2
	v_mov_b32_e32 v105, v2
	v_mov_b32_e32 v110, v2
	v_mov_b32_e32 v111, v2
	v_mov_b32_e32 v112, v2
	v_mov_b32_e32 v113, v2
	v_mov_b32_e32 v118, v2
	v_mov_b32_e32 v119, v2
	v_mov_b32_e32 v120, v2
	v_mov_b32_e32 v121, v2
	v_mov_b32_e32 v126, v2
	v_mov_b32_e32 v127, v2
	v_mov_b32_e32 v128, v2
	v_mov_b32_e32 v129, v2
	s_branch .LBB0_283
.Lpz_up:
	s_add_u32 s26, s22, 0xfffc0080
	s_addc_u32 s27, s23, -1
	s_add_i32 s69, 0, 0x10000
	s_cmp_eq_u32 s68, 12
	s_cselect_b32 s45, s30, s27
	s_cselect_b32 s44, s37, s26
	v_add_u32_e32 v156, s69, v152
	s_cselect_b32 s27, s13, s65
	s_cselect_b32 s26, s47, s56
	s_add_i32 s72, 0, 0x14000
	ds_read_b128 v[178:181], v156
	ds_read_b128 v[182:185], v156 offset:1024
	ds_read_b128 v[186:189], v156 offset:2048
	ds_read_b128 v[190:193], v156 offset:3072
	v_add_u32_e32 v156, s72, v152
	ds_read_b128 v[194:197], v156
	ds_read_b128 v[198:201], v156 offset:1024
	ds_read_b128 v[202:205], v156 offset:2048
	ds_read_b128 v[206:209], v156 offset:3072
	v_lshl_add_u64 v[156:157], s[22:23], 0, v[148:149]
	s_add_i32 m0, s50, 0xc000
	ds_read_b128 v[210:213], v155
	ds_read_b128 v[214:217], v155 offset:1024
	ds_read_b128 v[218:221], v155 offset:2048
	ds_read_b128 v[222:225], v155 offset:3072
	ds_read_b128 v[226:229], v155 offset:4096
	ds_read_b128 v[230:233], v155 offset:5120
	ds_read_b128 v[234:237], v155 offset:6144
	ds_read_b128 v[238:241], v155 offset:7168
	global_load_lds_dwordx4 v[156:157], off
	v_lshl_add_u64 v[156:157], s[22:23], 0, v[150:151]
	s_add_i32 m0, s50, 0xe000
	s_nop 0
	global_load_lds_dwordx4 v[156:157], off
	s_waitcnt vmcnt(16)
	s_waitcnt lgkmcnt(0)
	s_barrier
	s_setprio 1
	s_waitcnt lgkmcnt(0)
	v_mfma_f32_16x16x32_bf16 v[126:129], v[178:181], v[210:213], 0
	v_mfma_f32_16x16x32_bf16 v[118:121], v[186:189], v[210:213], 0
	v_mfma_f32_16x16x32_bf16 v[110:113], v[178:181], v[218:221], 0
	v_mfma_f32_16x16x32_bf16 v[102:105], v[186:189], v[218:221], 0
	v_mfma_f32_16x16x32_bf16 v[94:97], v[178:181], v[226:229], 0
	v_mfma_f32_16x16x32_bf16 v[86:89], v[186:189], v[226:229], 0
	v_mfma_f32_16x16x32_bf16 v[78:81], v[178:181], v[234:237], 0
	v_mfma_f32_16x16x32_bf16 v[70:73], v[186:189], v[234:237], 0
	v_mfma_f32_16x16x32_bf16 v[126:129], v[182:185], v[214:217], v[126:129]
	v_mfma_f32_16x16x32_bf16 v[118:121], v[190:193], v[214:217], v[118:121]
	v_mfma_f32_16x16x32_bf16 v[110:113], v[182:185], v[222:225], v[110:113]
	v_mfma_f32_16x16x32_bf16 v[102:105], v[190:193], v[222:225], v[102:105]
	v_mfma_f32_16x16x32_bf16 v[94:97], v[182:185], v[230:233], v[94:97]
	v_mfma_f32_16x16x32_bf16 v[86:89], v[190:193], v[230:233], v[86:89]
	v_mfma_f32_16x16x32_bf16 v[78:81], v[182:185], v[238:241], v[78:81]
	v_mfma_f32_16x16x32_bf16 v[70:73], v[190:193], v[238:241], v[70:73]
	s_setprio 0
	s_setprio 1
	v_mfma_f32_16x16x32_bf16 v[122:125], v[194:197], v[210:213], 0
	v_mfma_f32_16x16x32_bf16 v[114:117], v[202:205], v[210:213], 0
	v_mfma_f32_16x16x32_bf16 v[106:109], v[194:197], v[218:221], 0
	v_mfma_f32_16x16x32_bf16 v[98:101], v[202:205], v[218:221], 0
	v_mfma_f32_16x16x32_bf16 v[90:93], v[194:197], v[226:229], 0
	v_mfma_f32_16x16x32_bf16 v[82:85], v[202:205], v[226:229], 0
	v_mfma_f32_16x16x32_bf16 v[74:77], v[194:197], v[234:237], 0
	v_mfma_f32_16x16x32_bf16 v[66:69], v[202:205], v[234:237], 0
	v_mfma_f32_16x16x32_bf16 v[122:125], v[198:201], v[214:217], v[122:125]
	v_mfma_f32_16x16x32_bf16 v[114:117], v[206:209], v[214:217], v[114:117]
	v_mfma_f32_16x16x32_bf16 v[106:109], v[198:201], v[222:225], v[106:109]
	v_mfma_f32_16x16x32_bf16 v[98:101], v[206:209], v[222:225], v[98:101]
	s_setprio 2
	s_barrier
	v_mfma_f32_16x16x32_bf16 v[90:93], v[198:201], v[230:233], v[90:93]
	v_mfma_f32_16x16x32_bf16 v[82:85], v[206:209], v[230:233], v[82:85]
	v_mfma_f32_16x16x32_bf16 v[74:77], v[198:201], v[238:241], v[74:77]
	v_mfma_f32_16x16x32_bf16 v[66:69], v[206:209], v[238:241], v[66:69]
	s_setprio 0
	s_add_i32 s69, s69, s31
	v_lshl_add_u64 v[156:157], s[26:27], 0, v[134:135]
	s_mov_b32 m0, s69
	ds_read_b128 v[210:213], v155 offset:16384
	ds_read_b128 v[214:217], v155 offset:17408
	ds_read_b128 v[218:221], v155 offset:18432
	ds_read_b128 v[222:225], v155 offset:19456
	ds_read_b128 v[226:229], v155 offset:20480
	ds_read_b128 v[230:233], v155 offset:21504
	ds_read_b128 v[234:237], v155 offset:22528
	ds_read_b128 v[238:241], v155 offset:23552
	global_load_lds_dwordx4 v[156:157], off
	s_add_i32 m0, s69, 0x2000
	s_add_u32 s70, s26, 0x40000
	v_lshl_add_u64 v[160:161], s[26:27], 0, v[132:133]
	s_addc_u32 s71, s27, 0
	s_add_i32 s69, s72, s31
	global_load_lds_dwordx4 v[160:161], off
	v_lshl_add_u64 v[164:165], s[70:71], 0, v[134:135]
	s_mov_b32 m0, s69
	v_lshl_add_u64 v[242:243], s[44:45], 0, v[144:145]
	global_load_lds_dwordx4 v[164:165], off
	v_lshl_add_u64 v[164:165], s[70:71], 0, v[132:133]
	s_add_i32 m0, s69, 0x2000
	s_nop 0
	global_load_lds_dwordx4 v[164:165], off
	v_lshl_add_u64 v[164:165], s[44:45], 0, v[146:147]
	s_mov_b32 m0, s50
	s_nop 0
	global_load_lds_dwordx4 v[164:165], off
	s_mov_b32 m0, s51
	s_nop 0
	global_load_lds_dwordx4 v[242:243], off
	s_waitcnt vmcnt(16)
	s_waitcnt lgkmcnt(0)
	s_barrier
	s_setprio 1
	s_waitcnt lgkmcnt(0)
	v_mfma_f32_16x16x32_bf16 v[62:65], v[178:181], v[210:213], 0
	v_mfma_f32_16x16x32_bf16 v[54:57], v[186:189], v[210:213], 0
	v_mfma_f32_16x16x32_bf16 v[46:49], v[178:181], v[218:221], 0
	v_mfma_f32_16x16x32_bf16 v[38:41], v[186:189], v[218:221], 0
	v_mfma_f32_16x16x32_bf16 v[30:33], v[178:181], v[226:229], 0
	v_mfma_f32_16x16x32_bf16 v[22:25], v[186:189], v[226:229], 0
	v_mfma_f32_16x16x32_bf16 v[14:17], v[178:181], v[234:237], 0
	v_mfma_f32_16x16x32_bf16 v[6:9], v[186:189], v[234:237], 0
	v_mfma_f32_16x16x32_bf16 v[62:65], v[182:185], v[214:217], v[62:65]
	v_mfma_f32_16x16x32_bf16 v[54:57], v[190:193], v[214:217], v[54:57]
	v_mfma_f32_16x16x32_bf16 v[46:49], v[182:185], v[222:225], v[46:49]
	v_mfma_f32_16x16x32_bf16 v[38:41], v[190:193], v[222:225], v[38:41]
	v_mfma_f32_16x16x32_bf16 v[30:33], v[182:185], v[230:233], v[30:33]
	v_mfma_f32_16x16x32_bf16 v[22:25], v[190:193], v[230:233], v[22:25]
	v_mfma_f32_16x16x32_bf16 v[14:17], v[182:185], v[238:241], v[14:17]
	v_mfma_f32_16x16x32_bf16 v[6:9], v[190:193], v[238:241], v[6:9]
	s_setprio 0
	s_setprio 1
	v_mfma_f32_16x16x32_bf16 v[58:61], v[194:197], v[210:213], 0
	v_mfma_f32_16x16x32_bf16 v[50:53], v[202:205], v[210:213], 0
	v_mfma_f32_16x16x32_bf16 v[42:45], v[194:197], v[218:221], 0
	v_mfma_f32_16x16x32_bf16 v[34:37], v[202:205], v[218:221], 0
	v_mfma_f32_16x16x32_bf16 v[26:29], v[194:197], v[226:229], 0
	v_mfma_f32_16x16x32_bf16 v[18:21], v[202:205], v[226:229], 0
	v_mfma_f32_16x16x32_bf16 v[10:13], v[194:197], v[234:237], 0
	v_mfma_f32_16x16x32_bf16 v[2:5], v[202:205], v[234:237], 0
	v_mfma_f32_16x16x32_bf16 v[58:61], v[198:201], v[214:217], v[58:61]
	v_mfma_f32_16x16x32_bf16 v[50:53], v[206:209], v[214:217], v[50:53]
	v_mfma_f32_16x16x32_bf16 v[42:45], v[198:201], v[222:225], v[42:45]
	v_mfma_f32_16x16x32_bf16 v[34:37], v[206:209], v[222:225], v[34:37]
	s_setprio 2
	s_barrier
	v_mfma_f32_16x16x32_bf16 v[26:29], v[198:201], v[230:233], v[26:29]
	v_mfma_f32_16x16x32_bf16 v[18:21], v[206:209], v[230:233], v[18:21]
	v_mfma_f32_16x16x32_bf16 v[10:13], v[198:201], v[238:241], v[10:13]
	v_mfma_f32_16x16x32_bf16 v[2:5], v[206:209], v[238:241], v[2:5]
	s_setprio 0
	s_add_i32 s69, 0, 0x18000
	v_add_u32_e32 v159, s69, v152
	s_add_i32 s70, 0, 0x1c000
	ds_read_b128 v[178:181], v159
	ds_read_b128 v[182:185], v159 offset:1024
	ds_read_b128 v[186:189], v159 offset:2048
	ds_read_b128 v[190:193], v159 offset:3072
	v_add_u32_e32 v159, s70, v152
	ds_read_b128 v[194:197], v159
	ds_read_b128 v[198:201], v159 offset:1024
	ds_read_b128 v[202:205], v159 offset:2048
	ds_read_b128 v[206:209], v159 offset:3072
	s_add_u32 s44, s44, 0x40000
	s_addc_u32 s45, s45, 0
	s_mov_b32 m0, s52
	v_lshl_add_u64 v[244:245], s[44:45], 0, v[146:147]
	ds_read_b128 v[210:213], v155 offset:32768
	ds_read_b128 v[214:217], v155 offset:33792
	ds_read_b128 v[218:221], v155 offset:34816
	ds_read_b128 v[222:225], v155 offset:35840
	ds_read_b128 v[226:229], v155 offset:36864
	ds_read_b128 v[230:233], v155 offset:37888
	ds_read_b128 v[234:237], v155 offset:38912
	ds_read_b128 v[238:241], v155 offset:39936
	global_load_lds_dwordx4 v[244:245], off
	v_lshl_add_u64 v[244:245], s[44:45], 0, v[144:145]
	s_mov_b32 m0, s53
	s_nop 0
	global_load_lds_dwordx4 v[244:245], off
	s_waitcnt vmcnt(8)
	s_waitcnt lgkmcnt(0)
	s_barrier
	s_setprio 1
	s_waitcnt lgkmcnt(0)
	v_mfma_f32_16x16x32_bf16 v[126:129], v[178:181], v[210:213], v[126:129]
	v_mfma_f32_16x16x32_bf16 v[118:121], v[186:189], v[210:213], v[118:121]
	v_mfma_f32_16x16x32_bf16 v[110:113], v[178:181], v[218:221], v[110:113]
	v_mfma_f32_16x16x32_bf16 v[102:105], v[186:189], v[218:221], v[102:105]
	v_mfma_f32_16x16x32_bf16 v[94:97], v[178:181], v[226:229], v[94:97]
	v_mfma_f32_16x16x32_bf16 v[86:89], v[186:189], v[226:229], v[86:89]
	v_mfma_f32_16x16x32_bf16 v[78:81], v[178:181], v[234:237], v[78:81]
	v_mfma_f32_16x16x32_bf16 v[70:73], v[186:189], v[234:237], v[70:73]
	v_mfma_f32_16x16x32_bf16 v[126:129], v[182:185], v[214:217], v[126:129]
	v_mfma_f32_16x16x32_bf16 v[118:121], v[190:193], v[214:217], v[118:121]
	v_mfma_f32_16x16x32_bf16 v[110:113], v[182:185], v[222:225], v[110:113]
	v_mfma_f32_16x16x32_bf16 v[102:105], v[190:193], v[222:225], v[102:105]
	v_mfma_f32_16x16x32_bf16 v[94:97], v[182:185], v[230:233], v[94:97]
	v_mfma_f32_16x16x32_bf16 v[86:89], v[190:193], v[230:233], v[86:89]
	v_mfma_f32_16x16x32_bf16 v[78:81], v[182:185], v[238:241], v[78:81]
	v_mfma_f32_16x16x32_bf16 v[70:73], v[190:193], v[238:241], v[70:73]
	s_setprio 0
	s_setprio 1
	v_mfma_f32_16x16x32_bf16 v[122:125], v[194:197], v[210:213], v[122:125]
	v_mfma_f32_16x16x32_bf16 v[114:117], v[202:205], v[210:213], v[114:117]
	v_mfma_f32_16x16x32_bf16 v[106:109], v[194:197], v[218:221], v[106:109]
	v_mfma_f32_16x16x32_bf16 v[98:101], v[202:205], v[218:221], v[98:101]
	v_mfma_f32_16x16x32_bf16 v[90:93], v[194:197], v[226:229], v[90:93]
	v_mfma_f32_16x16x32_bf16 v[82:85], v[202:205], v[226:229], v[82:85]
	v_mfma_f32_16x16x32_bf16 v[74:77], v[194:197], v[234:237], v[74:77]
	v_mfma_f32_16x16x32_bf16 v[66:69], v[202:205], v[234:237], v[66:69]
	v_mfma_f32_16x16x32_bf16 v[122:125], v[198:201], v[214:217], v[122:125]
	v_mfma_f32_16x16x32_bf16 v[114:117], v[206:209], v[214:217], v[114:117]
	v_mfma_f32_16x16x32_bf16 v[106:109], v[198:201], v[222:225], v[106:109]
	v_mfma_f32_16x16x32_bf16 v[98:101], v[206:209], v[222:225], v[98:101]
	s_setprio 2
	s_barrier
	v_mfma_f32_16x16x32_bf16 v[90:93], v[198:201], v[230:233], v[90:93]
	v_mfma_f32_16x16x32_bf16 v[82:85], v[206:209], v[230:233], v[82:85]
	v_mfma_f32_16x16x32_bf16 v[74:77], v[198:201], v[238:241], v[74:77]
	v_mfma_f32_16x16x32_bf16 v[66:69], v[206:209], v[238:241], v[66:69]
	s_setprio 0
	s_add_i32 s44, s69, s31
	v_lshl_add_u64 v[156:157], v[156:157], 0, s[66:67]
	s_mov_b32 m0, s44
	ds_read_b128 v[210:213], v155 offset:49152
	ds_read_b128 v[214:217], v155 offset:50176
	ds_read_b128 v[218:221], v155 offset:51200
	ds_read_b128 v[222:225], v155 offset:52224
	ds_read_b128 v[226:229], v155 offset:53248
	ds_read_b128 v[230:233], v155 offset:54272
	ds_read_b128 v[234:237], v155 offset:55296
	ds_read_b128 v[238:241], v155 offset:56320
	global_load_lds_dwordx4 v[156:157], off
	s_add_i32 m0, s44, 0x2000
	s_add_u32 s26, s26, 0x40080
	v_lshl_add_u64 v[156:157], v[160:161], 0, s[66:67]
	s_addc_u32 s27, s27, 0
	s_add_i32 s44, s70, s31
	global_load_lds_dwordx4 v[156:157], off
	v_lshl_add_u64 v[156:157], s[26:27], 0, v[134:135]
	s_mov_b32 m0, s44
	s_nop 0
	global_load_lds_dwordx4 v[156:157], off
	v_lshl_add_u64 v[156:157], s[26:27], 0, v[132:133]
	s_add_i32 m0, s44, 0x2000
	s_nop 0
	global_load_lds_dwordx4 v[156:157], off
	v_lshl_add_u64 v[156:157], v[164:165], 0, s[66:67]
	s_mov_b32 m0, s19
	s_nop 0
	global_load_lds_dwordx4 v[156:157], off
	v_lshl_add_u64 v[156:157], v[242:243], 0, s[66:67]
	s_mov_b32 m0, s60
	s_nop 0
	global_load_lds_dwordx4 v[156:157], off
	s_waitcnt vmcnt(8)
	s_waitcnt lgkmcnt(0)
	s_barrier
	s_setprio 1
	s_waitcnt lgkmcnt(0)
	v_mfma_f32_16x16x32_bf16 v[62:65], v[178:181], v[210:213], v[62:65]
	v_mfma_f32_16x16x32_bf16 v[54:57], v[186:189], v[210:213], v[54:57]
	v_mfma_f32_16x16x32_bf16 v[46:49], v[178:181], v[218:221], v[46:49]
	v_mfma_f32_16x16x32_bf16 v[38:41], v[186:189], v[218:221], v[38:41]
	v_mfma_f32_16x16x32_bf16 v[30:33], v[178:181], v[226:229], v[30:33]
	v_mfma_f32_16x16x32_bf16 v[22:25], v[186:189], v[226:229], v[22:25]
	v_mfma_f32_16x16x32_bf16 v[14:17], v[178:181], v[234:237], v[14:17]
	v_mfma_f32_16x16x32_bf16 v[6:9], v[186:189], v[234:237], v[6:9]
	v_mfma_f32_16x16x32_bf16 v[62:65], v[182:185], v[214:217], v[62:65]
	v_mfma_f32_16x16x32_bf16 v[54:57], v[190:193], v[214:217], v[54:57]
	v_mfma_f32_16x16x32_bf16 v[46:49], v[182:185], v[222:225], v[46:49]
	v_mfma_f32_16x16x32_bf16 v[38:41], v[190:193], v[222:225], v[38:41]
	v_mfma_f32_16x16x32_bf16 v[30:33], v[182:185], v[230:233], v[30:33]
	v_mfma_f32_16x16x32_bf16 v[22:25], v[190:193], v[230:233], v[22:25]
	v_mfma_f32_16x16x32_bf16 v[14:17], v[182:185], v[238:241], v[14:17]
	v_mfma_f32_16x16x32_bf16 v[6:9], v[190:193], v[238:241], v[6:9]
	s_setprio 0
	s_setprio 1
	v_mfma_f32_16x16x32_bf16 v[58:61], v[194:197], v[210:213], v[58:61]
	v_mfma_f32_16x16x32_bf16 v[50:53], v[202:205], v[210:213], v[50:53]
	v_mfma_f32_16x16x32_bf16 v[42:45], v[194:197], v[218:221], v[42:45]
	v_mfma_f32_16x16x32_bf16 v[34:37], v[202:205], v[218:221], v[34:37]
	v_mfma_f32_16x16x32_bf16 v[26:29], v[194:197], v[226:229], v[26:29]
	v_mfma_f32_16x16x32_bf16 v[18:21], v[202:205], v[226:229], v[18:21]
	v_mfma_f32_16x16x32_bf16 v[10:13], v[194:197], v[234:237], v[10:13]
	v_mfma_f32_16x16x32_bf16 v[2:5], v[202:205], v[234:237], v[2:5]
	v_mfma_f32_16x16x32_bf16 v[58:61], v[198:201], v[214:217], v[58:61]
	v_mfma_f32_16x16x32_bf16 v[50:53], v[206:209], v[214:217], v[50:53]
	v_mfma_f32_16x16x32_bf16 v[42:45], v[198:201], v[222:225], v[42:45]
	v_mfma_f32_16x16x32_bf16 v[34:37], v[206:209], v[222:225], v[34:37]
	s_setprio 2
	s_barrier
	v_mfma_f32_16x16x32_bf16 v[26:29], v[198:201], v[230:233], v[26:29]
	v_mfma_f32_16x16x32_bf16 v[18:21], v[206:209], v[230:233], v[18:21]
	v_mfma_f32_16x16x32_bf16 v[10:13], v[198:201], v[238:241], v[10:13]
	v_mfma_f32_16x16x32_bf16 v[2:5], v[206:209], v[238:241], v[2:5]
	s_setprio 0
	s_add_i32 s68, s68, 2
	s_add_u32 s22, s22, 0x100
	s_addc_u32 s23, s23, 0
	s_add_u32 s56, s56, 0x100
	s_addc_u32 s65, s65, 0
	s_cmp_gt_u32 s68, 13

.LBB0_317:
	s_add_u32 s12, s12, 0x80
	s_addc_u32 s13, s13, 0
	s_add_u32 s24, s22, 0x100
	v_mov_b32_e32 v2, 0
	s_addc_u32 s25, s23, 0
	s_mov_b32 s22, 0
	v_readlane_b32 s30, v253, 0
	s_nop 1
	s_cmp_eq_u32 s30, 0
	s_cbranch_scc0 .Lpz_res
	v_mov_b32_e32 v3, v2
	v_mov_b32_e32 v4, v2
	v_mov_b32_e32 v5, v2
	v_mov_b32_e32 v6, v2
	v_mov_b32_e32 v7, v2
	v_mov_b32_e32 v8, v2
	v_mov_b32_e32 v9, v2
	v_mov_b32_e32 v18, v2
	v_mov_b32_e32 v19, v2
	v_mov_b32_e32 v20, v2
	v_mov_b32_e32 v21, v2
	v_mov_b32_e32 v22, v2
	v_mov_b32_e32 v23, v2
	v_mov_b32_e32 v24, v2
	v_mov_b32_e32 v25, v2
	v_mov_b32_e32 v34, v2
	v_mov_b32_e32 v35, v2
	v_mov_b32_e32 v36, v2
	v_mov_b32_e32 v37, v2
	v_mov_b32_e32 v38, v2
	v_mov_b32_e32 v39, v2
	v_mov_b32_e32 v40, v2
	v_mov_b32_e32 v41, v2
	v_mov_b32_e32 v50, v2
	v_mov_b32_e32 v51, v2
	v_mov_b32_e32 v52, v2
	v_mov_b32_e32 v53, v2
	v_mov_b32_e32 v54, v2
	v_mov_b32_e32 v55, v2
	v_mov_b32_e32 v56, v2
	v_mov_b32_e32 v57, v2
	v_mov_b32_e32 v10, v2
	v_mov_b32_e32 v11, v2
	v_mov_b32_e32 v12, v2
	v_mov_b32_e32 v13, v2
	v_mov_b32_e32 v14, v2
	v_mov_b32_e32 v15, v2
	v_mov_b32_e32 v16, v2
	v_mov_b32_e32 v17, v2
	v_mov_b32_e32 v26, v2
	v_mov_b32_e32 v27, v2
	v_mov_b32_e32 v28, v2
	v_mov_b32_e32 v29, v2
	v_mov_b32_e32 v30, v2
	v_mov_b32_e32 v31, v2
	v_mov_b32_e32 v32, v2
	v_mov_b32_e32 v33, v2
	v_mov_b32_e32 v42, v2
	v_mov_b32_e32 v43, v2
	v_mov_b32_e32 v44, v2
	v_mov_b32_e32 v45, v2
	v_mov_b32_e32 v46, v2
	v_mov_b32_e32 v47, v2
	v_mov_b32_e32 v48, v2
	v_mov_b32_e32 v49, v2
	v_mov_b32_e32 v58, v2
	v_mov_b32_e32 v59, v2
	v_mov_b32_e32 v60, v2
	v_mov_b32_e32 v61, v2
	v_mov_b32_e32 v62, v2
	v_mov_b32_e32 v63, v2
	v_mov_b32_e32 v64, v2
	v_mov_b32_e32 v65, v2
	v_mov_b32_e32 v66, v2
	v_mov_b32_e32 v67, v2
	v_mov_b32_e32 v68, v2
	v_mov_b32_e32 v69, v2
	v_mov_b32_e32 v70, v2
	v_mov_b32_e32 v71, v2
	v_mov_b32_e32 v72, v2
	v_mov_b32_e32 v73, v2
	v_mov_b32_e32 v82, v2
	v_mov_b32_e32 v83, v2
	v_mov_b32_e32 v84, v2
	v_mov_b32_e32 v85, v2
	v_mov_b32_e32 v86, v2
	v_mov_b32_e32 v87, v2
	v_mov_b32_e32 v88, v2
	v_mov_b32_e32 v89, v2
	v_mov_b32_e32 v98, v2
	v_mov_b32_e32 v99, v2
	v_mov_b32_e32 v100, v2
	v_mov_b32_e32 v101, v2
	v_mov_b32_e32 v102, v2
	v_mov_b32_e32 v103, v2
	v_mov_b32_e32 v104, v2
	v_mov_b32_e32 v105, v2
	v_mov_b32_e32 v114, v2
	v_mov_b32_e32 v115, v2
	v_mov_b32_e32 v116, v2
	v_mov_b32_e32 v117, v2
	v_mov_b32_e32 v118, v2
	v_mov_b32_e32 v119, v2
	v_mov_b32_e32 v120, v2
	v_mov_b32_e32 v121, v2
	v_mov_b32_e32 v74, v2
	v_mov_b32_e32 v75, v2
	v_mov_b32_e32 v76, v2
	v_mov_b32_e32 v77, v2
	v_mov_b32_e32 v78, v2
	v_mov_b32_e32 v79, v2
	v_mov_b32_e32 v80, v2
	v_mov_b32_e32 v81, v2
	v_mov_b32_e32 v90, v2
	v_mov_b32_e32 v91, v2
	v_mov_b32_e32 v92, v2
	v_mov_b32_e32 v93, v2
	v_mov_b32_e32 v94, v2
	v_mov_b32_e32 v95, v2
	v_mov_b32_e32 v96, v2
	v_mov_b32_e32 v97, v2
	v_mov_b32_e32 v106, v2
	v_mov_b32_e32 v107, v2
	v_mov_b32_e32 v108, v2
	v_mov_b32_e32 v109, v2
	v_mov_b32_e32 v110, v2
	v_mov_b32_e32 v111, v2
	v_mov_b32_e32 v112, v2
	v_mov_b32_e32 v113, v2
	v_mov_b32_e32 v122, v2
	v_mov_b32_e32 v123, v2
	v_mov_b32_e32 v124, v2
	v_mov_b32_e32 v125, v2
	v_mov_b32_e32 v126, v2
	v_mov_b32_e32 v127, v2
	v_mov_b32_e32 v128, v2
	v_mov_b32_e32 v129, v2
	s_branch .LBB0_318
.Lpz_res:
	s_add_i32 s30, s22, 2
	s_add_u32 s37, s12, 0x80
	s_addc_u32 s23, s13, 0
	s_add_i32 s56, 0, 0x10000
	s_cmp_eq_u32 s5, s22
	s_cselect_b32 s23, s11, s23
	s_cselect_b32 s22, s10, s37
	v_add_u32_e32 v156, s56, v159
	s_cselect_b32 s69, s99, s25
	s_cselect_b32 s68, s98, s24
	s_add_i32 s37, 0, 0x14000
	ds_read_b128 v[152:155], v156
	ds_read_b128 v[178:181], v156 offset:1024
	ds_read_b128 v[182:185], v156 offset:2048
	ds_read_b128 v[186:189], v156 offset:3072
	v_add_u32_e32 v156, s37, v159
	ds_read_b128 v[190:193], v156
	ds_read_b128 v[194:197], v156 offset:1024
	ds_read_b128 v[198:201], v156 offset:2048
	ds_read_b128 v[202:205], v156 offset:3072
	v_lshl_add_u64 v[156:157], s[12:13], 0, v[148:149]
	s_add_i32 m0, s45, 0xc000
	ds_read_b128 v[206:209], v161
	ds_read_b128 v[210:213], v161 offset:1024
	ds_read_b128 v[214:217], v161 offset:2048
	ds_read_b128 v[218:221], v161 offset:3072
	ds_read_b128 v[222:225], v161 offset:4096
	ds_read_b128 v[226:229], v161 offset:5120
	ds_read_b128 v[230:233], v161 offset:6144
	ds_read_b128 v[234:237], v161 offset:7168
	global_load_lds_dwordx4 v[156:157], off
	v_lshl_add_u64 v[156:157], s[12:13], 0, v[150:151]
	s_add_i32 m0, s45, 0xe000
	s_nop 0
	global_load_lds_dwordx4 v[156:157], off
	s_waitcnt vmcnt(32)
	s_waitcnt lgkmcnt(0)
	s_barrier
	s_setprio 1
	s_waitcnt lgkmcnt(0)
	v_mfma_f32_16x16x32_bf16 v[126:129], v[152:155], v[206:209], 0
	v_mfma_f32_16x16x32_bf16 v[122:125], v[182:185], v[206:209], 0
	v_mfma_f32_16x16x32_bf16 v[110:113], v[152:155], v[214:217], 0
	v_mfma_f32_16x16x32_bf16 v[106:109], v[182:185], v[214:217], 0
	v_mfma_f32_16x16x32_bf16 v[94:97], v[152:155], v[222:225], 0
	v_mfma_f32_16x16x32_bf16 v[90:93], v[182:185], v[222:225], 0
	v_mfma_f32_16x16x32_bf16 v[78:81], v[152:155], v[230:233], 0
	v_mfma_f32_16x16x32_bf16 v[74:77], v[182:185], v[230:233], 0
	v_mfma_f32_16x16x32_bf16 v[126:129], v[178:181], v[210:213], v[126:129]
	v_mfma_f32_16x16x32_bf16 v[122:125], v[186:189], v[210:213], v[122:125]
	v_mfma_f32_16x16x32_bf16 v[110:113], v[178:181], v[218:221], v[110:113]
	v_mfma_f32_16x16x32_bf16 v[106:109], v[186:189], v[218:221], v[106:109]
	v_mfma_f32_16x16x32_bf16 v[94:97], v[178:181], v[226:229], v[94:97]
	v_mfma_f32_16x16x32_bf16 v[90:93], v[186:189], v[226:229], v[90:93]
	v_mfma_f32_16x16x32_bf16 v[78:81], v[178:181], v[234:237], v[78:81]
	v_mfma_f32_16x16x32_bf16 v[74:77], v[186:189], v[234:237], v[74:77]
	s_setprio 0
	s_setprio 1
	v_mfma_f32_16x16x32_bf16 v[118:121], v[190:193], v[206:209], 0
	v_mfma_f32_16x16x32_bf16 v[114:117], v[198:201], v[206:209], 0
	v_mfma_f32_16x16x32_bf16 v[102:105], v[190:193], v[214:217], 0
	v_mfma_f32_16x16x32_bf16 v[98:101], v[198:201], v[214:217], 0
	v_mfma_f32_16x16x32_bf16 v[86:89], v[190:193], v[222:225], 0
	v_mfma_f32_16x16x32_bf16 v[82:85], v[198:201], v[222:225], 0
	v_mfma_f32_16x16x32_bf16 v[70:73], v[190:193], v[230:233], 0
	v_mfma_f32_16x16x32_bf16 v[66:69], v[198:201], v[230:233], 0
	v_mfma_f32_16x16x32_bf16 v[118:121], v[194:197], v[210:213], v[118:121]
	v_mfma_f32_16x16x32_bf16 v[114:117], v[202:205], v[210:213], v[114:117]
	v_mfma_f32_16x16x32_bf16 v[102:105], v[194:197], v[218:221], v[102:105]
	v_mfma_f32_16x16x32_bf16 v[98:101], v[202:205], v[218:221], v[98:101]
	s_setprio 2
	s_barrier
	v_mfma_f32_16x16x32_bf16 v[86:89], v[194:197], v[226:229], v[86:89]
	v_mfma_f32_16x16x32_bf16 v[82:85], v[202:205], v[226:229], v[82:85]
	v_mfma_f32_16x16x32_bf16 v[70:73], v[194:197], v[234:237], v[70:73]
	v_mfma_f32_16x16x32_bf16 v[66:69], v[202:205], v[234:237], v[66:69]
	s_setprio 0
	s_add_i32 s56, s56, s26
	v_lshl_add_u64 v[156:157], s[68:69], 0, v[134:135]
	s_mov_b32 m0, s56
	ds_read_b128 v[206:209], v161 offset:16384
	ds_read_b128 v[210:213], v161 offset:17408
	ds_read_b128 v[214:217], v161 offset:18432
	ds_read_b128 v[218:221], v161 offset:19456
	ds_read_b128 v[222:225], v161 offset:20480
	ds_read_b128 v[226:229], v161 offset:21504
	ds_read_b128 v[230:233], v161 offset:22528
	ds_read_b128 v[234:237], v161 offset:23552
	global_load_lds_dwordx4 v[156:157], off
	s_add_i32 m0, s56, 0x2000
	v_lshl_add_u64 v[164:165], s[68:69], 0, v[132:133]
	s_add_u32 s68, s68, s92
	s_addc_u32 s69, s69, 0
	s_add_i32 s37, s37, s26
	global_load_lds_dwordx4 v[164:165], off
	v_lshl_add_u64 v[238:239], s[68:69], 0, v[134:135]
	s_mov_b32 m0, s37
	v_lshl_add_u64 v[240:241], s[68:69], 0, v[132:133]
	global_load_lds_dwordx4 v[238:239], off
	s_add_i32 m0, s37, 0x2000
	v_lshl_add_u64 v[242:243], s[22:23], 0, v[146:147]
	global_load_lds_dwordx4 v[240:241], off
	s_mov_b32 m0, s45
	v_lshl_add_u64 v[244:245], s[22:23], 0, v[144:145]
	global_load_lds_dwordx4 v[242:243], off
	s_mov_b32 m0, s46
	s_nop 0
	global_load_lds_dwordx4 v[244:245], off
	s_waitcnt vmcnt(32)
	s_waitcnt lgkmcnt(0)
	s_barrier
	s_setprio 1
	s_waitcnt lgkmcnt(0)
	v_mfma_f32_16x16x32_bf16 v[62:65], v[152:155], v[206:209], 0
	v_mfma_f32_16x16x32_bf16 v[58:61], v[182:185], v[206:209], 0
	v_mfma_f32_16x16x32_bf16 v[46:49], v[152:155], v[214:217], 0
	v_mfma_f32_16x16x32_bf16 v[42:45], v[182:185], v[214:217], 0
	v_mfma_f32_16x16x32_bf16 v[30:33], v[152:155], v[222:225], 0
	v_mfma_f32_16x16x32_bf16 v[26:29], v[182:185], v[222:225], 0
	v_mfma_f32_16x16x32_bf16 v[14:17], v[152:155], v[230:233], 0
	v_mfma_f32_16x16x32_bf16 v[10:13], v[182:185], v[230:233], 0
	v_mfma_f32_16x16x32_bf16 v[62:65], v[178:181], v[210:213], v[62:65]
	v_mfma_f32_16x16x32_bf16 v[58:61], v[186:189], v[210:213], v[58:61]
	v_mfma_f32_16x16x32_bf16 v[46:49], v[178:181], v[218:221], v[46:49]
	v_mfma_f32_16x16x32_bf16 v[42:45], v[186:189], v[218:221], v[42:45]
	v_mfma_f32_16x16x32_bf16 v[30:33], v[178:181], v[226:229], v[30:33]
	v_mfma_f32_16x16x32_bf16 v[26:29], v[186:189], v[226:229], v[26:29]
	v_mfma_f32_16x16x32_bf16 v[14:17], v[178:181], v[234:237], v[14:17]
	v_mfma_f32_16x16x32_bf16 v[10:13], v[186:189], v[234:237], v[10:13]
	s_setprio 0
	s_setprio 1
	v_mfma_f32_16x16x32_bf16 v[54:57], v[190:193], v[206:209], 0
	v_mfma_f32_16x16x32_bf16 v[50:53], v[198:201], v[206:209], 0
	v_mfma_f32_16x16x32_bf16 v[38:41], v[190:193], v[214:217], 0
	v_mfma_f32_16x16x32_bf16 v[34:37], v[198:201], v[214:217], 0
	v_mfma_f32_16x16x32_bf16 v[22:25], v[190:193], v[222:225], 0
	v_mfma_f32_16x16x32_bf16 v[18:21], v[198:201], v[222:225], 0
	v_mfma_f32_16x16x32_bf16 v[6:9], v[190:193], v[230:233], 0
	v_mfma_f32_16x16x32_bf16 v[2:5], v[198:201], v[230:233], 0
	v_mfma_f32_16x16x32_bf16 v[54:57], v[194:197], v[210:213], v[54:57]
	v_mfma_f32_16x16x32_bf16 v[50:53], v[202:205], v[210:213], v[50:53]
	v_mfma_f32_16x16x32_bf16 v[38:41], v[194:197], v[218:221], v[38:41]
	v_mfma_f32_16x16x32_bf16 v[34:37], v[202:205], v[218:221], v[34:37]
	s_setprio 2
	s_barrier
	v_mfma_f32_16x16x32_bf16 v[22:25], v[194:197], v[226:229], v[22:25]
	v_mfma_f32_16x16x32_bf16 v[18:21], v[202:205], v[226:229], v[18:21]
	v_mfma_f32_16x16x32_bf16 v[6:9], v[194:197], v[234:237], v[6:9]
	v_mfma_f32_16x16x32_bf16 v[2:5], v[202:205], v[234:237], v[2:5]
	s_setprio 0
	s_add_i32 s37, 0, 0x18000
	v_add_u32_e32 v162, s37, v159
	s_add_i32 s56, 0, 0x1c000
	ds_read_b128 v[152:155], v162
	ds_read_b128 v[178:181], v162 offset:1024
	ds_read_b128 v[182:185], v162 offset:2048
	ds_read_b128 v[186:189], v162 offset:3072
	v_add_u32_e32 v162, s56, v159
	ds_read_b128 v[190:193], v162
	ds_read_b128 v[194:197], v162 offset:1024
	ds_read_b128 v[198:201], v162 offset:2048
	ds_read_b128 v[202:205], v162 offset:3072
	s_add_u32 s22, s22, s92
	s_addc_u32 s23, s23, 0
	s_mov_b32 m0, s47
	v_lshl_add_u64 v[246:247], s[22:23], 0, v[146:147]
	ds_read_b128 v[206:209], v161 offset:32768
	ds_read_b128 v[210:213], v161 offset:33792
	ds_read_b128 v[214:217], v161 offset:34816
	ds_read_b128 v[218:221], v161 offset:35840
	ds_read_b128 v[222:225], v161 offset:36864
	ds_read_b128 v[226:229], v161 offset:37888
	ds_read_b128 v[230:233], v161 offset:38912
	ds_read_b128 v[234:237], v161 offset:39936
	global_load_lds_dwordx4 v[246:247], off
	v_lshl_add_u64 v[246:247], s[22:23], 0, v[144:145]
	s_mov_b32 m0, s50
	s_nop 0
	global_load_lds_dwordx4 v[246:247], off
	s_waitcnt vmcnt(8)
	s_waitcnt lgkmcnt(0)
	s_barrier
	s_setprio 1
	s_waitcnt lgkmcnt(0)
	v_mfma_f32_16x16x32_bf16 v[126:129], v[152:155], v[206:209], v[126:129]
	v_mfma_f32_16x16x32_bf16 v[122:125], v[182:185], v[206:209], v[122:125]
	v_mfma_f32_16x16x32_bf16 v[110:113], v[152:155], v[214:217], v[110:113]
	v_mfma_f32_16x16x32_bf16 v[106:109], v[182:185], v[214:217], v[106:109]
	v_mfma_f32_16x16x32_bf16 v[94:97], v[152:155], v[222:225], v[94:97]
	v_mfma_f32_16x16x32_bf16 v[90:93], v[182:185], v[222:225], v[90:93]
	v_mfma_f32_16x16x32_bf16 v[78:81], v[152:155], v[230:233], v[78:81]
	v_mfma_f32_16x16x32_bf16 v[74:77], v[182:185], v[230:233], v[74:77]
	v_mfma_f32_16x16x32_bf16 v[126:129], v[178:181], v[210:213], v[126:129]
	v_mfma_f32_16x16x32_bf16 v[122:125], v[186:189], v[210:213], v[122:125]
	v_mfma_f32_16x16x32_bf16 v[110:113], v[178:181], v[218:221], v[110:113]
	v_mfma_f32_16x16x32_bf16 v[106:109], v[186:189], v[218:221], v[106:109]
	v_mfma_f32_16x16x32_bf16 v[94:97], v[178:181], v[226:229], v[94:97]
	v_mfma_f32_16x16x32_bf16 v[90:93], v[186:189], v[226:229], v[90:93]
	v_mfma_f32_16x16x32_bf16 v[78:81], v[178:181], v[234:237], v[78:81]
	v_mfma_f32_16x16x32_bf16 v[74:77], v[186:189], v[234:237], v[74:77]
	s_setprio 0
	s_setprio 1
	v_mfma_f32_16x16x32_bf16 v[118:121], v[190:193], v[206:209], v[118:121]
	v_mfma_f32_16x16x32_bf16 v[114:117], v[198:201], v[206:209], v[114:117]
	v_mfma_f32_16x16x32_bf16 v[102:105], v[190:193], v[214:217], v[102:105]
	v_mfma_f32_16x16x32_bf16 v[98:101], v[198:201], v[214:217], v[98:101]
	v_mfma_f32_16x16x32_bf16 v[86:89], v[190:193], v[222:225], v[86:89]
	v_mfma_f32_16x16x32_bf16 v[82:85], v[198:201], v[222:225], v[82:85]
	v_mfma_f32_16x16x32_bf16 v[70:73], v[190:193], v[230:233], v[70:73]
	v_mfma_f32_16x16x32_bf16 v[66:69], v[198:201], v[230:233], v[66:69]
	v_mfma_f32_16x16x32_bf16 v[118:121], v[194:197], v[210:213], v[118:121]
	v_mfma_f32_16x16x32_bf16 v[114:117], v[202:205], v[210:213], v[114:117]
	v_mfma_f32_16x16x32_bf16 v[102:105], v[194:197], v[218:221], v[102:105]
	v_mfma_f32_16x16x32_bf16 v[98:101], v[202:205], v[218:221], v[98:101]
	s_setprio 2
	s_barrier
	v_mfma_f32_16x16x32_bf16 v[86:89], v[194:197], v[226:229], v[86:89]
	v_mfma_f32_16x16x32_bf16 v[82:85], v[202:205], v[226:229], v[82:85]
	v_mfma_f32_16x16x32_bf16 v[70:73], v[194:197], v[234:237], v[70:73]
	v_mfma_f32_16x16x32_bf16 v[66:69], v[202:205], v[234:237], v[66:69]
	s_setprio 0
	s_add_i32 s22, s37, s26
	v_lshl_add_u64 v[156:157], v[156:157], 0, s[66:67]
	s_mov_b32 m0, s22
	ds_read_b128 v[206:209], v161 offset:49152
	ds_read_b128 v[210:213], v161 offset:50176
	ds_read_b128 v[214:217], v161 offset:51200
	ds_read_b128 v[218:221], v161 offset:52224
	ds_read_b128 v[222:225], v161 offset:53248
	ds_read_b128 v[226:229], v161 offset:54272
	ds_read_b128 v[230:233], v161 offset:55296
	ds_read_b128 v[234:237], v161 offset:56320
	global_load_lds_dwordx4 v[156:157], off
	v_lshl_add_u64 v[156:157], v[164:165], 0, s[66:67]
	s_add_i32 m0, s22, 0x2000
	s_add_i32 s22, s56, s26
	global_load_lds_dwordx4 v[156:157], off
	v_lshl_add_u64 v[156:157], v[238:239], 0, s[66:67]
	s_mov_b32 m0, s22
	s_nop 0
	global_load_lds_dwordx4 v[156:157], off
	v_lshl_add_u64 v[156:157], v[240:241], 0, s[66:67]
	s_add_i32 m0, s22, 0x2000
	s_nop 0
	global_load_lds_dwordx4 v[156:157], off
	v_lshl_add_u64 v[156:157], v[242:243], 0, s[66:67]
	s_mov_b32 m0, s51
	s_nop 0
	global_load_lds_dwordx4 v[156:157], off
	v_lshl_add_u64 v[156:157], v[244:245], 0, s[66:67]
	s_mov_b32 m0, s52
	s_nop 0
	global_load_lds_dwordx4 v[156:157], off
	s_waitcnt vmcnt(8)
	s_waitcnt lgkmcnt(0)
	s_barrier
	s_setprio 1
	s_waitcnt lgkmcnt(0)
	v_mfma_f32_16x16x32_bf16 v[62:65], v[152:155], v[206:209], v[62:65]
	v_mfma_f32_16x16x32_bf16 v[58:61], v[182:185], v[206:209], v[58:61]
	v_mfma_f32_16x16x32_bf16 v[46:49], v[152:155], v[214:217], v[46:49]
	v_mfma_f32_16x16x32_bf16 v[42:45], v[182:185], v[214:217], v[42:45]
	v_mfma_f32_16x16x32_bf16 v[30:33], v[152:155], v[222:225], v[30:33]
	v_mfma_f32_16x16x32_bf16 v[26:29], v[182:185], v[222:225], v[26:29]
	v_mfma_f32_16x16x32_bf16 v[14:17], v[152:155], v[230:233], v[14:17]
	v_mfma_f32_16x16x32_bf16 v[10:13], v[182:185], v[230:233], v[10:13]
	v_mfma_f32_16x16x32_bf16 v[62:65], v[178:181], v[210:213], v[62:65]
	v_mfma_f32_16x16x32_bf16 v[58:61], v[186:189], v[210:213], v[58:61]
	v_mfma_f32_16x16x32_bf16 v[46:49], v[178:181], v[218:221], v[46:49]
	v_mfma_f32_16x16x32_bf16 v[42:45], v[186:189], v[218:221], v[42:45]
	v_mfma_f32_16x16x32_bf16 v[30:33], v[178:181], v[226:229], v[30:33]
	v_mfma_f32_16x16x32_bf16 v[26:29], v[186:189], v[226:229], v[26:29]
	v_mfma_f32_16x16x32_bf16 v[14:17], v[178:181], v[234:237], v[14:17]
	v_mfma_f32_16x16x32_bf16 v[10:13], v[186:189], v[234:237], v[10:13]
	s_setprio 0
	s_setprio 1
	v_mfma_f32_16x16x32_bf16 v[54:57], v[190:193], v[206:209], v[54:57]
	v_mfma_f32_16x16x32_bf16 v[50:53], v[198:201], v[206:209], v[50:53]
	v_mfma_f32_16x16x32_bf16 v[38:41], v[190:193], v[214:217], v[38:41]
	v_mfma_f32_16x16x32_bf16 v[34:37], v[198:201], v[214:217], v[34:37]
	v_mfma_f32_16x16x32_bf16 v[22:25], v[190:193], v[222:225], v[22:25]
	v_mfma_f32_16x16x32_bf16 v[18:21], v[198:201], v[222:225], v[18:21]
	v_mfma_f32_16x16x32_bf16 v[6:9], v[190:193], v[230:233], v[6:9]
	v_mfma_f32_16x16x32_bf16 v[2:5], v[198:201], v[230:233], v[2:5]
	v_mfma_f32_16x16x32_bf16 v[54:57], v[194:197], v[210:213], v[54:57]
	v_mfma_f32_16x16x32_bf16 v[50:53], v[202:205], v[210:213], v[50:53]
	v_mfma_f32_16x16x32_bf16 v[38:41], v[194:197], v[218:221], v[38:41]
	v_mfma_f32_16x16x32_bf16 v[34:37], v[202:205], v[218:221], v[34:37]
	s_setprio 2
	s_barrier
	v_mfma_f32_16x16x32_bf16 v[22:25], v[194:197], v[226:229], v[22:25]
	v_mfma_f32_16x16x32_bf16 v[18:21], v[202:205], v[226:229], v[18:21]
	v_mfma_f32_16x16x32_bf16 v[6:9], v[194:197], v[234:237], v[6:9]
	v_mfma_f32_16x16x32_bf16 v[2:5], v[202:205], v[234:237], v[2:5]
	s_setprio 0
	s_add_u32 s12, s12, 0x100
	s_addc_u32 s13, s13, 0
	s_add_u32 s24, s24, 0x100
	s_addc_u32 s25, s25, 0
	s_cmp_ge_u32 s30, s4
	s_mov_b32 s22, s30

.LBB0_411:
	s_ashr_i32 s89, s88, 31
	s_lshl_b64 s[26:27], s[88:89], 19
	s_add_u32 s90, s78, s26
	s_addc_u32 s91, s79, s27
	s_and_b64 s[26:27], s[6:7], exec
	s_cselect_b32 s25, s91, s13
	s_cselect_b32 s30, s90, s12
	s_ashr_i32 s87, s86, 31
	s_lshl_b64 s[26:27], s[86:87], 19
	s_add_u32 s92, s4, s26
	s_addc_u32 s93, s5, s27
	s_and_b64 s[26:27], s[6:7], exec
	s_cselect_b32 s37, s93, s23
	s_cselect_b32 s47, s92, s22
	s_add_u32 s12, s12, 0x40080
	s_addc_u32 s13, s13, 0
	s_add_u32 s50, s22, 0x100
	v_mov_b32_e32 v2, 0
	s_addc_u32 s51, s23, 0
	s_mov_b32 s52, -2
	v_readlane_b32 s22, v253, 0
	s_nop 1
	s_cmp_eq_u32 s22, 0
	s_cbranch_scc0 .Lpz_ain
	v_mov_b32_e32 v3, v2
	v_mov_b32_e32 v4, v2
	v_mov_b32_e32 v5, v2
	v_mov_b32_e32 v6, v2
	v_mov_b32_e32 v7, v2
	v_mov_b32_e32 v8, v2
	v_mov_b32_e32 v9, v2
	v_mov_b32_e32 v14, v2
	v_mov_b32_e32 v15, v2
	v_mov_b32_e32 v16, v2
	v_mov_b32_e32 v17, v2
	v_mov_b32_e32 v22, v2
	v_mov_b32_e32 v23, v2
	v_mov_b32_e32 v24, v2
	v_mov_b32_e32 v25, v2
	v_mov_b32_e32 v30, v2
	v_mov_b32_e32 v31, v2
	v_mov_b32_e32 v32, v2
	v_mov_b32_e32 v33, v2
	v_mov_b32_e32 v38, v2
	v_mov_b32_e32 v39, v2
	v_mov_b32_e32 v40, v2
	v_mov_b32_e32 v41, v2
	v_mov_b32_e32 v46, v2
	v_mov_b32_e32 v47, v2
	v_mov_b32_e32 v48, v2
	v_mov_b32_e32 v49, v2
	v_mov_b32_e32 v54, v2
	v_mov_b32_e32 v55, v2
	v_mov_b32_e32 v56, v2
	v_mov_b32_e32 v57, v2
	v_mov_b32_e32 v10, v2
	v_mov_b32_e32 v11, v2
	v_mov_b32_e32 v12, v2
	v_mov_b32_e32 v13, v2
	v_mov_b32_e32 v18, v2
	v_mov_b32_e32 v19, v2
	v_mov_b32_e32 v20, v2
	v_mov_b32_e32 v21, v2
	v_mov_b32_e32 v26, v2
	v_mov_b32_e32 v27, v2
	v_mov_b32_e32 v28, v2
	v_mov_b32_e32 v29, v2
	v_mov_b32_e32 v34, v2
	v_mov_b32_e32 v35, v2
	v_mov_b32_e32 v36, v2
	v_mov_b32_e32 v37, v2
	v_mov_b32_e32 v42, v2
	v_mov_b32_e32 v43, v2
	v_mov_b32_e32 v44, v2
	v_mov_b32_e32 v45, v2
	v_mov_b32_e32 v50, v2
	v_mov_b32_e32 v51, v2
	v_mov_b32_e32 v52, v2
	v_mov_b32_e32 v53, v2
	v_mov_b32_e32 v58, v2
	v_mov_b32_e32 v59, v2
	v_mov_b32_e32 v60, v2
	v_mov_b32_e32 v61, v2
	v_mov_b32_e32 v62, v2
	v_mov_b32_e32 v63, v2
	v_mov_b32_e32 v64, v2
	v_mov_b32_e32 v65, v2
	v_mov_b32_e32 v66, v2
	v_mov_b32_e32 v67, v2
	v_mov_b32_e32 v68, v2
	v_mov_b32_e32 v69, v2
	v_mov_b32_e32 v70, v2
	v_mov_b32_e32 v71, v2
	v_mov_b32_e32 v72, v2
	v_mov_b32_e32 v73, v2
	v_mov_b32_e32 v78, v2
	v_mov_b32_e32 v79, v2
	v_mov_b32_e32 v80, v2
	v_mov_b32_e32 v81, v2
	v_mov_b32_e32 v86, v2
	v_mov_b32_e32 v87, v2
	v_mov_b32_e32 v88, v2
	v_mov_b32_e32 v89, v2
	v_mov_b32_e32 v94, v2
	v_mov_b32_e32 v95, v2
	v_mov_b32_e32 v96, v2
	v_mov_b32_e32 v97, v2
	v_mov_b32_e32 v102, v2
	v_mov_b32_e32 v103, v2
	v_mov_b32_e32 v104, v2
	v_mov_b32_e32 v105, v2
	v_mov_b32_e32 v114, v2
	v_mov_b32_e32 v115, v2
	v_mov_b32_e32 v116, v2
	v_mov_b32_e32 v117, v2
	v_mov_b32_e32 v118, v2
	v_mov_b32_e32 v119, v2
	v_mov_b32_e32 v120, v2
	v_mov_b32_e32 v121, v2
	v_mov_b32_e32 v74, v2
	v_mov_b32_e32 v75, v2
	v_mov_b32_e32 v76, v2
	v_mov_b32_e32 v77, v2
	v_mov_b32_e32 v82, v2
	v_mov_b32_e32 v83, v2
	v_mov_b32_e32 v84, v2
	v_mov_b32_e32 v85, v2
	v_mov_b32_e32 v90, v2
	v_mov_b32_e32 v91, v2
	v_mov_b32_e32 v92, v2
	v_mov_b32_e32 v93, v2
	v_mov_b32_e32 v98, v2
	v_mov_b32_e32 v99, v2
	v_mov_b32_e32 v100, v2
	v_mov_b32_e32 v101, v2
	v_mov_b32_e32 v106, v2
	v_mov_b32_e32 v107, v2
	v_mov_b32_e32 v108, v2
	v_mov_b32_e32 v109, v2
	v_mov_b32_e32 v110, v2
	v_mov_b32_e32 v111, v2
	v_mov_b32_e32 v112, v2
	v_mov_b32_e32 v113, v2
	v_mov_b32_e32 v122, v2
	v_mov_b32_e32 v123, v2
	v_mov_b32_e32 v124, v2
	v_mov_b32_e32 v125, v2
	v_mov_b32_e32 v126, v2
	v_mov_b32_e32 v127, v2
	v_mov_b32_e32 v128, v2
	v_mov_b32_e32 v129, v2
	s_branch .LBB0_412
.Lpz_ain:
	s_add_u32 s22, s12, 0xfffc0080
	s_addc_u32 s23, s13, -1
	s_add_i32 s53, 0, 0x10000
	s_cmp_eq_u32 s52, 12
	s_cselect_b32 s27, s25, s23
	s_cselect_b32 s26, s30, s22
	v_add_u32_e32 v134, s53, v178
	s_cselect_b32 s23, s37, s51
	s_cselect_b32 s22, s47, s50
	s_add_i32 s56, 0, 0x14000
	ds_read_b128 v[130:133], v134
	ds_read_b128 v[182:185], v134 offset:1024
	ds_read_b128 v[186:189], v134 offset:2048
	ds_read_b128 v[190:193], v134 offset:3072
	v_add_u32_e32 v134, s56, v178
	ds_read_b128 v[194:197], v134
	ds_read_b128 v[198:201], v134 offset:1024
	ds_read_b128 v[202:205], v134 offset:2048
	ds_read_b128 v[206:209], v134 offset:3072
	v_lshl_add_u64 v[160:161], s[12:13], 0, v[156:157]
	s_add_i32 m0, s31, 0xc000
	ds_read_b128 v[210:213], v180
	ds_read_b128 v[214:217], v180 offset:1024
	ds_read_b128 v[218:221], v180 offset:2048
	ds_read_b128 v[222:225], v180 offset:3072
	ds_read_b128 v[226:229], v180 offset:4096
	ds_read_b128 v[230:233], v180 offset:5120
	ds_read_b128 v[234:237], v180 offset:6144
	ds_read_b128 v[238:241], v180 offset:7168
	global_load_lds_dwordx4 v[160:161], off
	v_lshl_add_u64 v[160:161], s[12:13], 0, v[158:159]
	s_add_i32 m0, s31, 0xe000
	s_nop 0
	global_load_lds_dwordx4 v[160:161], off
	s_waitcnt vmcnt(16)
	s_waitcnt lgkmcnt(0)
	s_barrier
	s_setprio 1
	s_waitcnt lgkmcnt(0)
	v_mfma_f32_16x16x32_bf16 v[126:129], v[130:133], v[210:213], 0
	v_mfma_f32_16x16x32_bf16 v[122:125], v[186:189], v[210:213], 0
	v_mfma_f32_16x16x32_bf16 v[110:113], v[130:133], v[218:221], 0
	v_mfma_f32_16x16x32_bf16 v[106:109], v[186:189], v[218:221], 0
	v_mfma_f32_16x16x32_bf16 v[98:101], v[130:133], v[226:229], 0
	v_mfma_f32_16x16x32_bf16 v[90:93], v[186:189], v[226:229], 0
	v_mfma_f32_16x16x32_bf16 v[82:85], v[130:133], v[234:237], 0
	v_mfma_f32_16x16x32_bf16 v[74:77], v[186:189], v[234:237], 0
	v_mfma_f32_16x16x32_bf16 v[126:129], v[182:185], v[214:217], v[126:129]
	v_mfma_f32_16x16x32_bf16 v[122:125], v[190:193], v[214:217], v[122:125]
	v_mfma_f32_16x16x32_bf16 v[110:113], v[182:185], v[222:225], v[110:113]
	v_mfma_f32_16x16x32_bf16 v[106:109], v[190:193], v[222:225], v[106:109]
	v_mfma_f32_16x16x32_bf16 v[98:101], v[182:185], v[230:233], v[98:101]
	v_mfma_f32_16x16x32_bf16 v[90:93], v[190:193], v[230:233], v[90:93]
	v_mfma_f32_16x16x32_bf16 v[82:85], v[182:185], v[238:241], v[82:85]
	v_mfma_f32_16x16x32_bf16 v[74:77], v[190:193], v[238:241], v[74:77]
	s_setprio 0
	s_setprio 1
	v_mfma_f32_16x16x32_bf16 v[118:121], v[194:197], v[210:213], 0
	v_mfma_f32_16x16x32_bf16 v[114:117], v[202:205], v[210:213], 0
	v_mfma_f32_16x16x32_bf16 v[102:105], v[194:197], v[218:221], 0
	v_mfma_f32_16x16x32_bf16 v[94:97], v[202:205], v[218:221], 0
	v_mfma_f32_16x16x32_bf16 v[86:89], v[194:197], v[226:229], 0
	v_mfma_f32_16x16x32_bf16 v[78:81], v[202:205], v[226:229], 0
	v_mfma_f32_16x16x32_bf16 v[70:73], v[194:197], v[234:237], 0
	v_mfma_f32_16x16x32_bf16 v[66:69], v[202:205], v[234:237], 0
	v_mfma_f32_16x16x32_bf16 v[118:121], v[198:201], v[214:217], v[118:121]
	v_mfma_f32_16x16x32_bf16 v[114:117], v[206:209], v[214:217], v[114:117]
	v_mfma_f32_16x16x32_bf16 v[102:105], v[198:201], v[222:225], v[102:105]
	v_mfma_f32_16x16x32_bf16 v[94:97], v[206:209], v[222:225], v[94:97]
	s_setprio 2
	s_barrier
	v_mfma_f32_16x16x32_bf16 v[86:89], v[198:201], v[230:233], v[86:89]
	v_mfma_f32_16x16x32_bf16 v[78:81], v[206:209], v[230:233], v[78:81]
	v_mfma_f32_16x16x32_bf16 v[70:73], v[198:201], v[238:241], v[70:73]
	v_mfma_f32_16x16x32_bf16 v[66:69], v[206:209], v[238:241], v[66:69]
	s_setprio 0
	s_add_i32 s53, s53, s20
	v_lshl_add_u64 v[160:161], s[22:23], 0, v[148:149]
	s_mov_b32 m0, s53
	ds_read_b128 v[210:213], v180 offset:16384
	ds_read_b128 v[214:217], v180 offset:17408
	ds_read_b128 v[218:221], v180 offset:18432
	ds_read_b128 v[222:225], v180 offset:19456
	ds_read_b128 v[226:229], v180 offset:20480
	ds_read_b128 v[230:233], v180 offset:21504
	ds_read_b128 v[234:237], v180 offset:22528
	ds_read_b128 v[238:241], v180 offset:23552
	global_load_lds_dwordx4 v[160:161], off
	s_add_i32 m0, s53, 0x2000
	s_add_u32 s64, s22, 0x40000
	v_lshl_add_u64 v[164:165], s[22:23], 0, v[144:145]
	s_addc_u32 s65, s23, 0
	s_add_i32 s53, s56, s20
	global_load_lds_dwordx4 v[164:165], off
	v_lshl_add_u64 v[242:243], s[64:65], 0, v[148:149]
	s_mov_b32 m0, s53
	v_lshl_add_u64 v[244:245], s[26:27], 0, v[146:147]
	global_load_lds_dwordx4 v[242:243], off
	v_lshl_add_u64 v[242:243], s[64:65], 0, v[144:145]
	s_add_i32 m0, s53, 0x2000
	s_nop 0
	global_load_lds_dwordx4 v[242:243], off
	v_lshl_add_u64 v[242:243], s[26:27], 0, v[150:151]
	s_mov_b32 m0, s31
	s_nop 0
	global_load_lds_dwordx4 v[242:243], off
	s_mov_b32 m0, s35
	s_nop 0
	global_load_lds_dwordx4 v[244:245], off
	s_waitcnt vmcnt(16)
	s_waitcnt lgkmcnt(0)
	s_barrier
	s_setprio 1
	s_waitcnt lgkmcnt(0)
	v_mfma_f32_16x16x32_bf16 v[62:65], v[130:133], v[210:213], 0
	v_mfma_f32_16x16x32_bf16 v[58:61], v[186:189], v[210:213], 0
	v_mfma_f32_16x16x32_bf16 v[50:53], v[130:133], v[218:221], 0
	v_mfma_f32_16x16x32_bf16 v[42:45], v[186:189], v[218:221], 0
	v_mfma_f32_16x16x32_bf16 v[34:37], v[130:133], v[226:229], 0
	v_mfma_f32_16x16x32_bf16 v[26:29], v[186:189], v[226:229], 0
	v_mfma_f32_16x16x32_bf16 v[18:21], v[130:133], v[234:237], 0
	v_mfma_f32_16x16x32_bf16 v[10:13], v[186:189], v[234:237], 0
	v_mfma_f32_16x16x32_bf16 v[62:65], v[182:185], v[214:217], v[62:65]
	v_mfma_f32_16x16x32_bf16 v[58:61], v[190:193], v[214:217], v[58:61]
	v_mfma_f32_16x16x32_bf16 v[50:53], v[182:185], v[222:225], v[50:53]
	v_mfma_f32_16x16x32_bf16 v[42:45], v[190:193], v[222:225], v[42:45]
	v_mfma_f32_16x16x32_bf16 v[34:37], v[182:185], v[230:233], v[34:37]
	v_mfma_f32_16x16x32_bf16 v[26:29], v[190:193], v[230:233], v[26:29]
	v_mfma_f32_16x16x32_bf16 v[18:21], v[182:185], v[238:241], v[18:21]
	v_mfma_f32_16x16x32_bf16 v[10:13], v[190:193], v[238:241], v[10:13]
	s_setprio 0
	s_setprio 1
	v_mfma_f32_16x16x32_bf16 v[54:57], v[194:197], v[210:213], 0
	v_mfma_f32_16x16x32_bf16 v[46:49], v[202:205], v[210:213], 0
	v_mfma_f32_16x16x32_bf16 v[38:41], v[194:197], v[218:221], 0
	v_mfma_f32_16x16x32_bf16 v[30:33], v[202:205], v[218:221], 0
	v_mfma_f32_16x16x32_bf16 v[22:25], v[194:197], v[226:229], 0
	v_mfma_f32_16x16x32_bf16 v[14:17], v[202:205], v[226:229], 0
	v_mfma_f32_16x16x32_bf16 v[6:9], v[194:197], v[234:237], 0
	v_mfma_f32_16x16x32_bf16 v[2:5], v[202:205], v[234:237], 0
	v_mfma_f32_16x16x32_bf16 v[54:57], v[198:201], v[214:217], v[54:57]
	v_mfma_f32_16x16x32_bf16 v[46:49], v[206:209], v[214:217], v[46:49]
	v_mfma_f32_16x16x32_bf16 v[38:41], v[198:201], v[222:225], v[38:41]
	v_mfma_f32_16x16x32_bf16 v[30:33], v[206:209], v[222:225], v[30:33]
	s_setprio 2
	s_barrier
	v_mfma_f32_16x16x32_bf16 v[22:25], v[198:201], v[230:233], v[22:25]
	v_mfma_f32_16x16x32_bf16 v[14:17], v[206:209], v[230:233], v[14:17]
	v_mfma_f32_16x16x32_bf16 v[6:9], v[198:201], v[238:241], v[6:9]
	v_mfma_f32_16x16x32_bf16 v[2:5], v[206:209], v[238:241], v[2:5]
	s_setprio 0
	s_add_i32 s53, 0, 0x18000
	v_add_u32_e32 v134, s53, v178
	s_add_i32 s56, 0, 0x1c000
	ds_read_b128 v[130:133], v134
	ds_read_b128 v[182:185], v134 offset:1024
	ds_read_b128 v[186:189], v134 offset:2048
	ds_read_b128 v[190:193], v134 offset:3072
	v_add_u32_e32 v134, s56, v178
	ds_read_b128 v[194:197], v134
	ds_read_b128 v[198:201], v134 offset:1024
	ds_read_b128 v[202:205], v134 offset:2048
	ds_read_b128 v[206:209], v134 offset:3072
	s_add_u32 s26, s26, 0x40000
	s_addc_u32 s27, s27, 0
	s_mov_b32 m0, s38
	v_lshl_add_u64 v[246:247], s[26:27], 0, v[150:151]
	ds_read_b128 v[210:213], v180 offset:32768
	ds_read_b128 v[214:217], v180 offset:33792
	ds_read_b128 v[218:221], v180 offset:34816
	ds_read_b128 v[222:225], v180 offset:35840
	ds_read_b128 v[226:229], v180 offset:36864
	ds_read_b128 v[230:233], v180 offset:37888
	ds_read_b128 v[234:237], v180 offset:38912
	ds_read_b128 v[238:241], v180 offset:39936
	global_load_lds_dwordx4 v[246:247], off
	v_lshl_add_u64 v[246:247], s[26:27], 0, v[146:147]
	s_mov_b32 m0, s40
	s_nop 0
	global_load_lds_dwordx4 v[246:247], off
	s_waitcnt vmcnt(8)
	s_waitcnt lgkmcnt(0)
	s_barrier
	s_setprio 1
	s_waitcnt lgkmcnt(0)
	v_mfma_f32_16x16x32_bf16 v[126:129], v[130:133], v[210:213], v[126:129]
	v_mfma_f32_16x16x32_bf16 v[122:125], v[186:189], v[210:213], v[122:125]
	v_mfma_f32_16x16x32_bf16 v[110:113], v[130:133], v[218:221], v[110:113]
	v_mfma_f32_16x16x32_bf16 v[106:109], v[186:189], v[218:221], v[106:109]
	v_mfma_f32_16x16x32_bf16 v[98:101], v[130:133], v[226:229], v[98:101]
	v_mfma_f32_16x16x32_bf16 v[90:93], v[186:189], v[226:229], v[90:93]
	v_mfma_f32_16x16x32_bf16 v[82:85], v[130:133], v[234:237], v[82:85]
	v_mfma_f32_16x16x32_bf16 v[74:77], v[186:189], v[234:237], v[74:77]
	v_mfma_f32_16x16x32_bf16 v[126:129], v[182:185], v[214:217], v[126:129]
	v_mfma_f32_16x16x32_bf16 v[122:125], v[190:193], v[214:217], v[122:125]
	v_mfma_f32_16x16x32_bf16 v[110:113], v[182:185], v[222:225], v[110:113]
	v_mfma_f32_16x16x32_bf16 v[106:109], v[190:193], v[222:225], v[106:109]
	v_mfma_f32_16x16x32_bf16 v[98:101], v[182:185], v[230:233], v[98:101]
	v_mfma_f32_16x16x32_bf16 v[90:93], v[190:193], v[230:233], v[90:93]
	v_mfma_f32_16x16x32_bf16 v[82:85], v[182:185], v[238:241], v[82:85]
	v_mfma_f32_16x16x32_bf16 v[74:77], v[190:193], v[238:241], v[74:77]
	s_setprio 0
	s_setprio 1
	v_mfma_f32_16x16x32_bf16 v[118:121], v[194:197], v[210:213], v[118:121]
	v_mfma_f32_16x16x32_bf16 v[114:117], v[202:205], v[210:213], v[114:117]
	v_mfma_f32_16x16x32_bf16 v[102:105], v[194:197], v[218:221], v[102:105]
	v_mfma_f32_16x16x32_bf16 v[94:97], v[202:205], v[218:221], v[94:97]
	v_mfma_f32_16x16x32_bf16 v[86:89], v[194:197], v[226:229], v[86:89]
	v_mfma_f32_16x16x32_bf16 v[78:81], v[202:205], v[226:229], v[78:81]
	v_mfma_f32_16x16x32_bf16 v[70:73], v[194:197], v[234:237], v[70:73]
	v_mfma_f32_16x16x32_bf16 v[66:69], v[202:205], v[234:237], v[66:69]
	v_mfma_f32_16x16x32_bf16 v[118:121], v[198:201], v[214:217], v[118:121]
	v_mfma_f32_16x16x32_bf16 v[114:117], v[206:209], v[214:217], v[114:117]
	v_mfma_f32_16x16x32_bf16 v[102:105], v[198:201], v[222:225], v[102:105]
	v_mfma_f32_16x16x32_bf16 v[94:97], v[206:209], v[222:225], v[94:97]
	s_setprio 2
	s_barrier
	v_mfma_f32_16x16x32_bf16 v[86:89], v[198:201], v[230:233], v[86:89]
	v_mfma_f32_16x16x32_bf16 v[78:81], v[206:209], v[230:233], v[78:81]
	v_mfma_f32_16x16x32_bf16 v[70:73], v[198:201], v[238:241], v[70:73]
	v_mfma_f32_16x16x32_bf16 v[66:69], v[206:209], v[238:241], v[66:69]
	s_setprio 0
	s_add_i32 s26, s53, s20
	v_lshl_add_u64 v[160:161], v[160:161], 0, s[66:67]
	s_mov_b32 m0, s26
	ds_read_b128 v[210:213], v180 offset:49152
	ds_read_b128 v[214:217], v180 offset:50176
	ds_read_b128 v[218:221], v180 offset:51200
	ds_read_b128 v[222:225], v180 offset:52224
	ds_read_b128 v[226:229], v180 offset:53248
	ds_read_b128 v[230:233], v180 offset:54272
	ds_read_b128 v[234:237], v180 offset:55296
	ds_read_b128 v[238:241], v180 offset:56320
	global_load_lds_dwordx4 v[160:161], off
	s_add_i32 m0, s26, 0x2000
	s_add_u32 s22, s22, 0x40080
	v_lshl_add_u64 v[160:161], v[164:165], 0, s[66:67]
	s_addc_u32 s23, s23, 0
	s_add_i32 s26, s56, s20
	global_load_lds_dwordx4 v[160:161], off
	v_lshl_add_u64 v[160:161], s[22:23], 0, v[148:149]
	s_mov_b32 m0, s26
	s_nop 0
	global_load_lds_dwordx4 v[160:161], off
	v_lshl_add_u64 v[160:161], s[22:23], 0, v[144:145]
	s_add_i32 m0, s26, 0x2000
	s_nop 0
	global_load_lds_dwordx4 v[160:161], off
	v_lshl_add_u64 v[160:161], v[242:243], 0, s[66:67]
	s_mov_b32 m0, s41
	s_nop 0
	global_load_lds_dwordx4 v[160:161], off
	v_lshl_add_u64 v[160:161], v[244:245], 0, s[66:67]
	s_mov_b32 m0, s44
	s_nop 0
	global_load_lds_dwordx4 v[160:161], off
	s_waitcnt vmcnt(8)
	s_waitcnt lgkmcnt(0)
	s_barrier
	s_setprio 1
	s_waitcnt lgkmcnt(0)
	v_mfma_f32_16x16x32_bf16 v[62:65], v[130:133], v[210:213], v[62:65]
	v_mfma_f32_16x16x32_bf16 v[58:61], v[186:189], v[210:213], v[58:61]
	v_mfma_f32_16x16x32_bf16 v[50:53], v[130:133], v[218:221], v[50:53]
	v_mfma_f32_16x16x32_bf16 v[42:45], v[186:189], v[218:221], v[42:45]
	v_mfma_f32_16x16x32_bf16 v[34:37], v[130:133], v[226:229], v[34:37]
	v_mfma_f32_16x16x32_bf16 v[26:29], v[186:189], v[226:229], v[26:29]
	v_mfma_f32_16x16x32_bf16 v[18:21], v[130:133], v[234:237], v[18:21]
	v_mfma_f32_16x16x32_bf16 v[10:13], v[186:189], v[234:237], v[10:13]
	v_mfma_f32_16x16x32_bf16 v[62:65], v[182:185], v[214:217], v[62:65]
	v_mfma_f32_16x16x32_bf16 v[58:61], v[190:193], v[214:217], v[58:61]
	v_mfma_f32_16x16x32_bf16 v[50:53], v[182:185], v[222:225], v[50:53]
	v_mfma_f32_16x16x32_bf16 v[42:45], v[190:193], v[222:225], v[42:45]
	v_mfma_f32_16x16x32_bf16 v[34:37], v[182:185], v[230:233], v[34:37]
	v_mfma_f32_16x16x32_bf16 v[26:29], v[190:193], v[230:233], v[26:29]
	v_mfma_f32_16x16x32_bf16 v[18:21], v[182:185], v[238:241], v[18:21]
	v_mfma_f32_16x16x32_bf16 v[10:13], v[190:193], v[238:241], v[10:13]
	s_setprio 0
	s_setprio 1
	v_mfma_f32_16x16x32_bf16 v[54:57], v[194:197], v[210:213], v[54:57]
	v_mfma_f32_16x16x32_bf16 v[46:49], v[202:205], v[210:213], v[46:49]
	v_mfma_f32_16x16x32_bf16 v[38:41], v[194:197], v[218:221], v[38:41]
	v_mfma_f32_16x16x32_bf16 v[30:33], v[202:205], v[218:221], v[30:33]
	v_mfma_f32_16x16x32_bf16 v[22:25], v[194:197], v[226:229], v[22:25]
	v_mfma_f32_16x16x32_bf16 v[14:17], v[202:205], v[226:229], v[14:17]
	v_mfma_f32_16x16x32_bf16 v[6:9], v[194:197], v[234:237], v[6:9]
	v_mfma_f32_16x16x32_bf16 v[2:5], v[202:205], v[234:237], v[2:5]
	v_mfma_f32_16x16x32_bf16 v[54:57], v[198:201], v[214:217], v[54:57]
	v_mfma_f32_16x16x32_bf16 v[46:49], v[206:209], v[214:217], v[46:49]
	v_mfma_f32_16x16x32_bf16 v[38:41], v[198:201], v[222:225], v[38:41]
	v_mfma_f32_16x16x32_bf16 v[30:33], v[206:209], v[222:225], v[30:33]
	s_setprio 2
	s_barrier
	v_mfma_f32_16x16x32_bf16 v[22:25], v[198:201], v[230:233], v[22:25]
	v_mfma_f32_16x16x32_bf16 v[14:17], v[206:209], v[230:233], v[14:17]
	v_mfma_f32_16x16x32_bf16 v[6:9], v[198:201], v[238:241], v[6:9]
	v_mfma_f32_16x16x32_bf16 v[2:5], v[206:209], v[238:241], v[2:5]
	s_setprio 0
	s_add_i32 s52, s52, 2
	s_add_u32 s12, s12, 0x100
	s_addc_u32 s13, s13, 0
	s_add_u32 s50, s50, 0x100
	s_addc_u32 s51, s51, 0
	s_cmp_gt_u32 s52, 13
